# v14 + compute segments trimmed: no-op lgkmcnt waits between MFMAs deleted, trailing s_setprio 0 moved behind the closing barrier
# speedup vs baseline: 1.0056x; 1.0056x over previous
.LBB0_121:
	ds_read_b128 v[164:167], v131
	ds_read_b128 v[168:171], v131 offset:1024
	ds_read_b128 v[172:175], v131 offset:2048
	ds_read_b128 v[176:179], v131 offset:3072
	ds_read_b128 v[180:183], v160
	ds_read_b128 v[184:187], v160 offset:1024
	ds_read_b128 v[188:191], v160 offset:2048
	ds_read_b128 v[192:195], v160 offset:3072
	s_add_i32 s55, s52, 0xfffc0080
	s_cmp_eq_u32 s54, 12
	s_cselect_b32 s57, s16, s55
	s_cselect_b32 s56, s17, s53
	s_or_b32 s55, s57, 0x80
	s_mov_b32 m0, s40
	s_nop 0
	buffer_load_dwordx4 v156, s[12:15], s52 offen lds
	s_nop 0
	s_mov_b32 m0, s41
	s_nop 0
	buffer_load_dwordx4 v157, s[12:15], s52 offen lds
	ds_read_b128 v[196:199], v161
	ds_read_b128 v[200:203], v161 offset:1024
	ds_read_b128 v[204:207], v161 offset:2048
	ds_read_b128 v[208:211], v161 offset:3072
	ds_read_b128 v[212:215], v161 offset:4096
	ds_read_b128 v[216:219], v161 offset:5120
	ds_read_b128 v[220:223], v161 offset:6144
	ds_read_b128 v[224:227], v161 offset:7168
	s_waitcnt vmcnt(8)
	s_waitcnt lgkmcnt(0)
	s_barrier
	s_setprio 1
	v_mfma_f32_16x16x32_bf16 v[126:129], v[164:167], v[196:199], v[126:129]
	v_mfma_f32_16x16x32_bf16 v[122:125], v[172:175], v[196:199], v[122:125]
	v_mfma_f32_16x16x32_bf16 v[118:121], v[164:167], v[204:207], v[118:121]
	v_mfma_f32_16x16x32_bf16 v[110:113], v[172:175], v[204:207], v[110:113]
	v_mfma_f32_16x16x32_bf16 v[102:105], v[164:167], v[212:215], v[102:105]
	v_mfma_f32_16x16x32_bf16 v[94:97], v[172:175], v[212:215], v[94:97]
	v_mfma_f32_16x16x32_bf16 v[86:89], v[164:167], v[220:223], v[86:89]
	v_mfma_f32_16x16x32_bf16 v[78:81], v[172:175], v[220:223], v[78:81]
	v_mfma_f32_16x16x32_bf16 v[126:129], v[168:171], v[200:203], v[126:129]
	v_mfma_f32_16x16x32_bf16 v[122:125], v[176:179], v[200:203], v[122:125]
	v_mfma_f32_16x16x32_bf16 v[118:121], v[168:171], v[208:211], v[118:121]
	v_mfma_f32_16x16x32_bf16 v[110:113], v[176:179], v[208:211], v[110:113]
	v_mfma_f32_16x16x32_bf16 v[102:105], v[168:171], v[216:219], v[102:105]
	v_mfma_f32_16x16x32_bf16 v[94:97], v[176:179], v[216:219], v[94:97]
	v_mfma_f32_16x16x32_bf16 v[86:89], v[168:171], v[224:227], v[86:89]
	v_mfma_f32_16x16x32_bf16 v[78:81], v[176:179], v[224:227], v[78:81]
	s_setprio 0
	s_setprio 1
	v_mfma_f32_16x16x32_bf16 v[114:117], v[180:183], v[196:199], v[114:117]
	v_mfma_f32_16x16x32_bf16 v[106:109], v[188:191], v[196:199], v[106:109]
	v_mfma_f32_16x16x32_bf16 v[98:101], v[180:183], v[204:207], v[98:101]
	v_mfma_f32_16x16x32_bf16 v[90:93], v[188:191], v[204:207], v[90:93]
	v_mfma_f32_16x16x32_bf16 v[82:85], v[180:183], v[212:215], v[82:85]
	v_mfma_f32_16x16x32_bf16 v[74:77], v[188:191], v[212:215], v[74:77]
	v_mfma_f32_16x16x32_bf16 v[70:73], v[180:183], v[220:223], v[70:73]
	v_mfma_f32_16x16x32_bf16 v[66:69], v[188:191], v[220:223], v[66:69]
	v_mfma_f32_16x16x32_bf16 v[114:117], v[184:187], v[200:203], v[114:117]
	v_mfma_f32_16x16x32_bf16 v[106:109], v[192:195], v[200:203], v[106:109]
	v_mfma_f32_16x16x32_bf16 v[98:101], v[184:187], v[208:211], v[98:101]
	v_mfma_f32_16x16x32_bf16 v[90:93], v[192:195], v[208:211], v[90:93]
	v_mfma_f32_16x16x32_bf16 v[82:85], v[184:187], v[216:219], v[82:85]
	v_mfma_f32_16x16x32_bf16 v[74:77], v[192:195], v[216:219], v[74:77]
	v_mfma_f32_16x16x32_bf16 v[70:73], v[184:187], v[224:227], v[70:73]
	v_mfma_f32_16x16x32_bf16 v[66:69], v[192:195], v[224:227], v[66:69]
	s_barrier
	s_setprio 0
	ds_read_b128 v[196:199], v161 offset:16384
	ds_read_b128 v[200:203], v161 offset:17408
	s_mov_b32 m0, s22
	s_nop 0
	buffer_load_dwordx4 v154, s[8:11], s56 offen lds
	ds_read_b128 v[204:207], v161 offset:18432
	ds_read_b128 v[208:211], v161 offset:19456
	s_add_i32 s58, s56, 0x40000
	s_mov_b32 m0, s23
	s_nop 0
	buffer_load_dwordx4 v155, s[8:11], s56 offen lds
	ds_read_b128 v[212:215], v161 offset:20480
	ds_read_b128 v[216:219], v161 offset:21504
	s_nop 0
	s_mov_b32 m0, s24
	s_nop 0
	buffer_load_dwordx4 v154, s[8:11], s58 offen lds
	ds_read_b128 v[220:223], v161 offset:22528
	ds_read_b128 v[224:227], v161 offset:23552
	s_nop 0
	s_mov_b32 m0, s25
	s_nop 0
	buffer_load_dwordx4 v155, s[8:11], s58 offen lds
	s_nop 0
	s_mov_b32 m0, s21
	s_nop 0
	buffer_load_dwordx4 v156, s[12:15], s57 offen lds
	s_nop 0
	s_mov_b32 m0, s27
	s_nop 0
	buffer_load_dwordx4 v157, s[12:15], s57 offen lds
	s_waitcnt vmcnt(8)
	s_waitcnt lgkmcnt(0)
	s_barrier
	s_setprio 1
	v_mfma_f32_16x16x32_bf16 v[62:65], v[164:167], v[196:199], v[62:65]
	v_mfma_f32_16x16x32_bf16 v[58:61], v[172:175], v[196:199], v[58:61]
	v_mfma_f32_16x16x32_bf16 v[54:57], v[164:167], v[204:207], v[54:57]
	v_mfma_f32_16x16x32_bf16 v[46:49], v[172:175], v[204:207], v[46:49]
	v_mfma_f32_16x16x32_bf16 v[38:41], v[164:167], v[212:215], v[38:41]
	v_mfma_f32_16x16x32_bf16 v[30:33], v[172:175], v[212:215], v[30:33]
	v_mfma_f32_16x16x32_bf16 v[22:25], v[164:167], v[220:223], v[22:25]
	v_mfma_f32_16x16x32_bf16 v[14:17], v[172:175], v[220:223], v[14:17]
	v_mfma_f32_16x16x32_bf16 v[62:65], v[168:171], v[200:203], v[62:65]
	v_mfma_f32_16x16x32_bf16 v[58:61], v[176:179], v[200:203], v[58:61]
	v_mfma_f32_16x16x32_bf16 v[54:57], v[168:171], v[208:211], v[54:57]
	v_mfma_f32_16x16x32_bf16 v[46:49], v[176:179], v[208:211], v[46:49]
	v_mfma_f32_16x16x32_bf16 v[38:41], v[168:171], v[216:219], v[38:41]
	v_mfma_f32_16x16x32_bf16 v[30:33], v[176:179], v[216:219], v[30:33]
	v_mfma_f32_16x16x32_bf16 v[22:25], v[168:171], v[224:227], v[22:25]
	v_mfma_f32_16x16x32_bf16 v[14:17], v[176:179], v[224:227], v[14:17]
	s_setprio 0
	s_setprio 1
	v_mfma_f32_16x16x32_bf16 v[50:53], v[180:183], v[196:199], v[50:53]
	v_mfma_f32_16x16x32_bf16 v[42:45], v[188:191], v[196:199], v[42:45]
	v_mfma_f32_16x16x32_bf16 v[34:37], v[180:183], v[204:207], v[34:37]
	v_mfma_f32_16x16x32_bf16 v[26:29], v[188:191], v[204:207], v[26:29]
	v_mfma_f32_16x16x32_bf16 v[18:21], v[180:183], v[212:215], v[18:21]
	v_mfma_f32_16x16x32_bf16 v[10:13], v[188:191], v[212:215], v[10:13]
	v_mfma_f32_16x16x32_bf16 v[6:9], v[180:183], v[220:223], v[6:9]
	v_mfma_f32_16x16x32_bf16 v[2:5], v[188:191], v[220:223], v[2:5]
	v_mfma_f32_16x16x32_bf16 v[50:53], v[184:187], v[200:203], v[50:53]
	v_mfma_f32_16x16x32_bf16 v[42:45], v[192:195], v[200:203], v[42:45]
	v_mfma_f32_16x16x32_bf16 v[34:37], v[184:187], v[208:211], v[34:37]
	v_mfma_f32_16x16x32_bf16 v[26:29], v[192:195], v[208:211], v[26:29]
	v_mfma_f32_16x16x32_bf16 v[18:21], v[184:187], v[216:219], v[18:21]
	v_mfma_f32_16x16x32_bf16 v[10:13], v[192:195], v[216:219], v[10:13]
	v_mfma_f32_16x16x32_bf16 v[6:9], v[184:187], v[224:227], v[6:9]
	v_mfma_f32_16x16x32_bf16 v[2:5], v[192:195], v[224:227], v[2:5]
	s_barrier
	s_setprio 0
	ds_read_b128 v[164:167], v162
	ds_read_b128 v[168:171], v162 offset:1024
	ds_read_b128 v[172:175], v162 offset:2048
	ds_read_b128 v[176:179], v162 offset:3072
	ds_read_b128 v[180:183], v163
	ds_read_b128 v[184:187], v163 offset:1024
	ds_read_b128 v[188:191], v163 offset:2048
	ds_read_b128 v[192:195], v163 offset:3072
	s_add_i32 s57, s57, 0x40000
	s_mov_b32 m0, s28
	s_nop 0
	buffer_load_dwordx4 v156, s[12:15], s57 offen lds
	s_nop 0
	s_mov_b32 m0, s30
	s_nop 0
	buffer_load_dwordx4 v157, s[12:15], s57 offen lds
	ds_read_b128 v[196:199], v161 offset:32768
	ds_read_b128 v[200:203], v161 offset:33792
	ds_read_b128 v[204:207], v161 offset:34816
	ds_read_b128 v[208:211], v161 offset:35840
	ds_read_b128 v[212:215], v161 offset:36864
	ds_read_b128 v[216:219], v161 offset:37888
	ds_read_b128 v[220:223], v161 offset:38912
	ds_read_b128 v[224:227], v161 offset:39936
	s_waitcnt vmcnt(8)
	s_waitcnt lgkmcnt(0)
	s_barrier
	s_setprio 1
	v_mfma_f32_16x16x32_bf16 v[126:129], v[164:167], v[196:199], v[126:129]
	v_mfma_f32_16x16x32_bf16 v[122:125], v[172:175], v[196:199], v[122:125]
	v_mfma_f32_16x16x32_bf16 v[118:121], v[164:167], v[204:207], v[118:121]
	v_mfma_f32_16x16x32_bf16 v[110:113], v[172:175], v[204:207], v[110:113]
	v_mfma_f32_16x16x32_bf16 v[102:105], v[164:167], v[212:215], v[102:105]
	v_mfma_f32_16x16x32_bf16 v[94:97], v[172:175], v[212:215], v[94:97]
	v_mfma_f32_16x16x32_bf16 v[86:89], v[164:167], v[220:223], v[86:89]
	v_mfma_f32_16x16x32_bf16 v[78:81], v[172:175], v[220:223], v[78:81]
	v_mfma_f32_16x16x32_bf16 v[126:129], v[168:171], v[200:203], v[126:129]
	v_mfma_f32_16x16x32_bf16 v[122:125], v[176:179], v[200:203], v[122:125]
	v_mfma_f32_16x16x32_bf16 v[118:121], v[168:171], v[208:211], v[118:121]
	v_mfma_f32_16x16x32_bf16 v[110:113], v[176:179], v[208:211], v[110:113]
	v_mfma_f32_16x16x32_bf16 v[102:105], v[168:171], v[216:219], v[102:105]
	v_mfma_f32_16x16x32_bf16 v[94:97], v[176:179], v[216:219], v[94:97]
	v_mfma_f32_16x16x32_bf16 v[86:89], v[168:171], v[224:227], v[86:89]
	v_mfma_f32_16x16x32_bf16 v[78:81], v[176:179], v[224:227], v[78:81]
	s_setprio 0
	s_setprio 1
	v_mfma_f32_16x16x32_bf16 v[114:117], v[180:183], v[196:199], v[114:117]
	v_mfma_f32_16x16x32_bf16 v[106:109], v[188:191], v[196:199], v[106:109]
	v_mfma_f32_16x16x32_bf16 v[98:101], v[180:183], v[204:207], v[98:101]
	v_mfma_f32_16x16x32_bf16 v[90:93], v[188:191], v[204:207], v[90:93]
	v_mfma_f32_16x16x32_bf16 v[82:85], v[180:183], v[212:215], v[82:85]
	v_mfma_f32_16x16x32_bf16 v[74:77], v[188:191], v[212:215], v[74:77]
	v_mfma_f32_16x16x32_bf16 v[70:73], v[180:183], v[220:223], v[70:73]
	v_mfma_f32_16x16x32_bf16 v[66:69], v[188:191], v[220:223], v[66:69]
	v_mfma_f32_16x16x32_bf16 v[114:117], v[184:187], v[200:203], v[114:117]
	v_mfma_f32_16x16x32_bf16 v[106:109], v[192:195], v[200:203], v[106:109]
	v_mfma_f32_16x16x32_bf16 v[98:101], v[184:187], v[208:211], v[98:101]
	v_mfma_f32_16x16x32_bf16 v[90:93], v[192:195], v[208:211], v[90:93]
	v_mfma_f32_16x16x32_bf16 v[82:85], v[184:187], v[216:219], v[82:85]
	v_mfma_f32_16x16x32_bf16 v[74:77], v[192:195], v[216:219], v[74:77]
	v_mfma_f32_16x16x32_bf16 v[70:73], v[184:187], v[224:227], v[70:73]
	v_mfma_f32_16x16x32_bf16 v[66:69], v[192:195], v[224:227], v[66:69]
	s_barrier
	s_setprio 0
	ds_read_b128 v[196:199], v161 offset:49152
	ds_read_b128 v[200:203], v161 offset:50176
	s_or_b32 s57, s56, 0x80
	s_mov_b32 m0, s34
	s_nop 0
	buffer_load_dwordx4 v154, s[8:11], s57 offen lds
	ds_read_b128 v[204:207], v161 offset:51200
	ds_read_b128 v[208:211], v161 offset:52224
	s_add_i32 s56, s56, 0x40080
	s_mov_b32 m0, s35
	s_nop 0
	buffer_load_dwordx4 v155, s[8:11], s57 offen lds
	ds_read_b128 v[212:215], v161 offset:53248
	ds_read_b128 v[216:219], v161 offset:54272
	s_nop 0
	s_mov_b32 m0, s38
	s_nop 0
	buffer_load_dwordx4 v154, s[8:11], s56 offen lds
	ds_read_b128 v[220:223], v161 offset:55296
	ds_read_b128 v[224:227], v161 offset:56320
	s_nop 0
	s_mov_b32 m0, s39
	s_nop 0
	buffer_load_dwordx4 v155, s[8:11], s56 offen lds
	s_nop 0
	s_mov_b32 m0, s36
	s_nop 0
	buffer_load_dwordx4 v156, s[12:15], s55 offen lds
	s_nop 0
	s_mov_b32 m0, s37
	s_nop 0
	buffer_load_dwordx4 v157, s[12:15], s55 offen lds
	s_waitcnt vmcnt(8)
	s_waitcnt lgkmcnt(0)
	s_barrier
	s_setprio 1
	v_mfma_f32_16x16x32_bf16 v[62:65], v[164:167], v[196:199], v[62:65]
	v_mfma_f32_16x16x32_bf16 v[58:61], v[172:175], v[196:199], v[58:61]
	v_mfma_f32_16x16x32_bf16 v[54:57], v[164:167], v[204:207], v[54:57]
	v_mfma_f32_16x16x32_bf16 v[46:49], v[172:175], v[204:207], v[46:49]
	v_mfma_f32_16x16x32_bf16 v[38:41], v[164:167], v[212:215], v[38:41]
	v_mfma_f32_16x16x32_bf16 v[30:33], v[172:175], v[212:215], v[30:33]
	v_mfma_f32_16x16x32_bf16 v[22:25], v[164:167], v[220:223], v[22:25]
	v_mfma_f32_16x16x32_bf16 v[14:17], v[172:175], v[220:223], v[14:17]
	v_mfma_f32_16x16x32_bf16 v[62:65], v[168:171], v[200:203], v[62:65]
	v_mfma_f32_16x16x32_bf16 v[58:61], v[176:179], v[200:203], v[58:61]
	v_mfma_f32_16x16x32_bf16 v[54:57], v[168:171], v[208:211], v[54:57]
	v_mfma_f32_16x16x32_bf16 v[46:49], v[176:179], v[208:211], v[46:49]
	v_mfma_f32_16x16x32_bf16 v[38:41], v[168:171], v[216:219], v[38:41]
	v_mfma_f32_16x16x32_bf16 v[30:33], v[176:179], v[216:219], v[30:33]
	v_mfma_f32_16x16x32_bf16 v[22:25], v[168:171], v[224:227], v[22:25]
	v_mfma_f32_16x16x32_bf16 v[14:17], v[176:179], v[224:227], v[14:17]
	s_setprio 0
	s_setprio 1
	v_mfma_f32_16x16x32_bf16 v[50:53], v[180:183], v[196:199], v[50:53]
	v_mfma_f32_16x16x32_bf16 v[42:45], v[188:191], v[196:199], v[42:45]
	v_mfma_f32_16x16x32_bf16 v[34:37], v[180:183], v[204:207], v[34:37]
	v_mfma_f32_16x16x32_bf16 v[26:29], v[188:191], v[204:207], v[26:29]
	v_mfma_f32_16x16x32_bf16 v[18:21], v[180:183], v[212:215], v[18:21]
	v_mfma_f32_16x16x32_bf16 v[10:13], v[188:191], v[212:215], v[10:13]
	v_mfma_f32_16x16x32_bf16 v[6:9], v[180:183], v[220:223], v[6:9]
	v_mfma_f32_16x16x32_bf16 v[2:5], v[188:191], v[220:223], v[2:5]
	v_mfma_f32_16x16x32_bf16 v[50:53], v[184:187], v[200:203], v[50:53]
	v_mfma_f32_16x16x32_bf16 v[42:45], v[192:195], v[200:203], v[42:45]
	v_mfma_f32_16x16x32_bf16 v[34:37], v[184:187], v[208:211], v[34:37]
	v_mfma_f32_16x16x32_bf16 v[26:29], v[192:195], v[208:211], v[26:29]
	v_mfma_f32_16x16x32_bf16 v[18:21], v[184:187], v[216:219], v[18:21]
	v_mfma_f32_16x16x32_bf16 v[10:13], v[192:195], v[216:219], v[10:13]
	v_mfma_f32_16x16x32_bf16 v[6:9], v[184:187], v[224:227], v[6:9]
	v_mfma_f32_16x16x32_bf16 v[2:5], v[192:195], v[224:227], v[2:5]
	s_barrier
	s_setprio 0
	s_add_i32 s54, s54, 2
	s_addk_i32 s52, 0x100
	s_addk_i32 s53, 0x100
	s_cmp_gt_u32 s54, 13
	s_cbranch_scc0 .LBB0_121
	s_and_b64 vcc, exec, s[6:7]
	s_cbranch_vccz .LBB0_126
	s_barrier
	s_cmp_gt_i32 s46, 3
	s_mov_b64 s[16:17], -1
	s_cbranch_scc1 .LBB0_127

.LBB0_223:
	v_add_u32_e32 v150, 0x10000, v132
	v_add_u32_e32 v166, 0x14000, v132
	ds_read_b128 v[134:137], v150
	ds_read_b128 v[142:145], v150 offset:1024
	ds_read_b128 v[146:149], v150 offset:2048
	ds_read_b128 v[150:153], v150 offset:3072
	ds_read_b128 v[154:157], v166
	ds_read_b128 v[158:161], v166 offset:1024
	ds_read_b128 v[162:165], v166 offset:2048
	ds_read_b128 v[166:169], v166 offset:3072
	s_add_i32 s63, s39, s60
	s_add_i32 s62, s34, s60
	s_add_i32 s61, s63, 0x800
	s_addk_i32 s62, 0x800
	s_cmp_eq_u32 s60, 0
	s_cselect_b32 s64, s55, s61
	s_cselect_b32 s62, s58, s62
	s_or_b32 s61, s64, 0x80
	s_add_i32 s63, s63, 0x40780
	s_mov_b32 m0, s49
	s_nop 0
	buffer_load_dwordx4 v130, s[12:15], s63 offen lds
	s_nop 0
	s_mov_b32 m0, s50
	s_nop 0
	buffer_load_dwordx4 v131, s[12:15], s63 offen lds
	ds_read_b128 v[170:173], v133
	ds_read_b128 v[174:177], v133 offset:1024
	ds_read_b128 v[178:181], v133 offset:2048
	ds_read_b128 v[182:185], v133 offset:3072
	ds_read_b128 v[186:189], v133 offset:4096
	ds_read_b128 v[190:193], v133 offset:5120
	ds_read_b128 v[194:197], v133 offset:6144
	ds_read_b128 v[198:201], v133 offset:7168
	s_waitcnt vmcnt(8)
	s_waitcnt lgkmcnt(0)
	s_barrier
	s_setprio 1
	v_mfma_f32_16x16x32_bf16 v[138:141], v[134:137], v[170:173], v[138:141]
	v_mfma_f32_16x16x32_bf16 v[126:129], v[146:149], v[170:173], v[126:129]
	v_mfma_f32_16x16x32_bf16 v[110:113], v[134:137], v[178:181], v[110:113]
	v_mfma_f32_16x16x32_bf16 v[106:109], v[146:149], v[178:181], v[106:109]
	v_mfma_f32_16x16x32_bf16 v[94:97], v[134:137], v[186:189], v[94:97]
	v_mfma_f32_16x16x32_bf16 v[90:93], v[146:149], v[186:189], v[90:93]
	v_mfma_f32_16x16x32_bf16 v[78:81], v[134:137], v[194:197], v[78:81]
	v_mfma_f32_16x16x32_bf16 v[74:77], v[146:149], v[194:197], v[74:77]
	v_mfma_f32_16x16x32_bf16 v[138:141], v[142:145], v[174:177], v[138:141]
	v_mfma_f32_16x16x32_bf16 v[126:129], v[150:153], v[174:177], v[126:129]
	v_mfma_f32_16x16x32_bf16 v[110:113], v[142:145], v[182:185], v[110:113]
	v_mfma_f32_16x16x32_bf16 v[106:109], v[150:153], v[182:185], v[106:109]
	v_mfma_f32_16x16x32_bf16 v[94:97], v[142:145], v[190:193], v[94:97]
	v_mfma_f32_16x16x32_bf16 v[90:93], v[150:153], v[190:193], v[90:93]
	v_mfma_f32_16x16x32_bf16 v[78:81], v[142:145], v[198:201], v[78:81]
	v_mfma_f32_16x16x32_bf16 v[74:77], v[150:153], v[198:201], v[74:77]
	s_setprio 0
	s_setprio 1
	v_mfma_f32_16x16x32_bf16 v[118:121], v[154:157], v[170:173], v[118:121]
	v_mfma_f32_16x16x32_bf16 v[114:117], v[162:165], v[170:173], v[114:117]
	v_mfma_f32_16x16x32_bf16 v[102:105], v[154:157], v[178:181], v[102:105]
	v_mfma_f32_16x16x32_bf16 v[98:101], v[162:165], v[178:181], v[98:101]
	v_mfma_f32_16x16x32_bf16 v[86:89], v[154:157], v[186:189], v[86:89]
	v_mfma_f32_16x16x32_bf16 v[82:85], v[162:165], v[186:189], v[82:85]
	v_mfma_f32_16x16x32_bf16 v[70:73], v[154:157], v[194:197], v[70:73]
	v_mfma_f32_16x16x32_bf16 v[66:69], v[162:165], v[194:197], v[66:69]
	v_mfma_f32_16x16x32_bf16 v[118:121], v[158:161], v[174:177], v[118:121]
	v_mfma_f32_16x16x32_bf16 v[114:117], v[166:169], v[174:177], v[114:117]
	v_mfma_f32_16x16x32_bf16 v[102:105], v[158:161], v[182:185], v[102:105]
	v_mfma_f32_16x16x32_bf16 v[98:101], v[166:169], v[182:185], v[98:101]
	v_mfma_f32_16x16x32_bf16 v[86:89], v[158:161], v[190:193], v[86:89]
	v_mfma_f32_16x16x32_bf16 v[82:85], v[166:169], v[190:193], v[82:85]
	v_mfma_f32_16x16x32_bf16 v[70:73], v[158:161], v[198:201], v[70:73]
	v_mfma_f32_16x16x32_bf16 v[66:69], v[166:169], v[198:201], v[66:69]
	s_barrier
	s_setprio 0
	ds_read_b128 v[170:173], v133 offset:16384
	ds_read_b128 v[174:177], v133 offset:17408
	s_mov_b32 m0, s33
	s_nop 0
	buffer_load_dwordx4 v130, s[8:11], s62 offen lds
	ds_read_b128 v[178:181], v133 offset:18432
	ds_read_b128 v[182:185], v133 offset:19456
	s_add_i32 s63, s62, 0x40000
	s_mov_b32 m0, s35
	s_nop 0
	buffer_load_dwordx4 v131, s[8:11], s62 offen lds
	ds_read_b128 v[186:189], v133 offset:20480
	ds_read_b128 v[190:193], v133 offset:21504
	s_nop 0
	s_mov_b32 m0, s36
	s_nop 0
	buffer_load_dwordx4 v130, s[8:11], s63 offen lds
	ds_read_b128 v[194:197], v133 offset:22528
	ds_read_b128 v[198:201], v133 offset:23552
	s_nop 0
	s_mov_b32 m0, s37
	s_nop 0
	buffer_load_dwordx4 v131, s[8:11], s63 offen lds
	s_nop 0
	s_mov_b32 m0, s31
	s_nop 0
	buffer_load_dwordx4 v130, s[12:15], s64 offen lds
	s_nop 0
	s_mov_b32 m0, s40
	s_nop 0
	buffer_load_dwordx4 v131, s[12:15], s64 offen lds
	s_waitcnt vmcnt(8)
	s_waitcnt lgkmcnt(0)
	s_barrier
	s_setprio 1
	v_mfma_f32_16x16x32_bf16 v[62:65], v[134:137], v[170:173], v[62:65]
	v_mfma_f32_16x16x32_bf16 v[58:61], v[146:149], v[170:173], v[58:61]
	v_mfma_f32_16x16x32_bf16 v[46:49], v[134:137], v[178:181], v[46:49]
	v_mfma_f32_16x16x32_bf16 v[42:45], v[146:149], v[178:181], v[42:45]
	v_mfma_f32_16x16x32_bf16 v[30:33], v[134:137], v[186:189], v[30:33]
	v_mfma_f32_16x16x32_bf16 v[26:29], v[146:149], v[186:189], v[26:29]
	v_mfma_f32_16x16x32_bf16 v[14:17], v[134:137], v[194:197], v[14:17]
	v_mfma_f32_16x16x32_bf16 v[10:13], v[146:149], v[194:197], v[10:13]
	v_mfma_f32_16x16x32_bf16 v[62:65], v[142:145], v[174:177], v[62:65]
	v_mfma_f32_16x16x32_bf16 v[58:61], v[150:153], v[174:177], v[58:61]
	v_mfma_f32_16x16x32_bf16 v[46:49], v[142:145], v[182:185], v[46:49]
	v_mfma_f32_16x16x32_bf16 v[42:45], v[150:153], v[182:185], v[42:45]
	v_mfma_f32_16x16x32_bf16 v[30:33], v[142:145], v[190:193], v[30:33]
	v_mfma_f32_16x16x32_bf16 v[26:29], v[150:153], v[190:193], v[26:29]
	v_mfma_f32_16x16x32_bf16 v[14:17], v[142:145], v[198:201], v[14:17]
	v_mfma_f32_16x16x32_bf16 v[10:13], v[150:153], v[198:201], v[10:13]
	s_setprio 0
	s_setprio 1
	v_mfma_f32_16x16x32_bf16 v[54:57], v[154:157], v[170:173], v[54:57]
	v_mfma_f32_16x16x32_bf16 v[50:53], v[162:165], v[170:173], v[50:53]
	v_mfma_f32_16x16x32_bf16 v[38:41], v[154:157], v[178:181], v[38:41]
	v_mfma_f32_16x16x32_bf16 v[34:37], v[162:165], v[178:181], v[34:37]
	v_mfma_f32_16x16x32_bf16 v[22:25], v[154:157], v[186:189], v[22:25]
	v_mfma_f32_16x16x32_bf16 v[18:21], v[162:165], v[186:189], v[18:21]
	v_mfma_f32_16x16x32_bf16 v[6:9], v[154:157], v[194:197], v[6:9]
	v_mfma_f32_16x16x32_bf16 v[2:5], v[162:165], v[194:197], v[2:5]
	v_mfma_f32_16x16x32_bf16 v[54:57], v[158:161], v[174:177], v[54:57]
	v_mfma_f32_16x16x32_bf16 v[50:53], v[166:169], v[174:177], v[50:53]
	v_mfma_f32_16x16x32_bf16 v[38:41], v[158:161], v[182:185], v[38:41]
	v_mfma_f32_16x16x32_bf16 v[34:37], v[166:169], v[182:185], v[34:37]
	v_mfma_f32_16x16x32_bf16 v[22:25], v[158:161], v[190:193], v[22:25]
	v_mfma_f32_16x16x32_bf16 v[18:21], v[166:169], v[190:193], v[18:21]
	v_mfma_f32_16x16x32_bf16 v[6:9], v[158:161], v[198:201], v[6:9]
	v_mfma_f32_16x16x32_bf16 v[2:5], v[166:169], v[198:201], v[2:5]
	s_barrier
	s_setprio 0
	v_add_u32_e32 v150, 0x18000, v132
	v_add_u32_e32 v166, 0x1c000, v132
	ds_read_b128 v[134:137], v150
	ds_read_b128 v[142:145], v150 offset:1024
	ds_read_b128 v[146:149], v150 offset:2048
	ds_read_b128 v[150:153], v150 offset:3072
	ds_read_b128 v[154:157], v166
	ds_read_b128 v[158:161], v166 offset:1024
	ds_read_b128 v[162:165], v166 offset:2048
	ds_read_b128 v[166:169], v166 offset:3072
	s_add_i32 s63, s64, 0x40000
	s_mov_b32 m0, s41
	s_nop 0
	buffer_load_dwordx4 v130, s[12:15], s63 offen lds
	s_nop 0
	s_mov_b32 m0, s42
	s_nop 0
	buffer_load_dwordx4 v131, s[12:15], s63 offen lds
	ds_read_b128 v[170:173], v133 offset:32768
	ds_read_b128 v[174:177], v133 offset:33792
	ds_read_b128 v[178:181], v133 offset:34816
	ds_read_b128 v[182:185], v133 offset:35840
	ds_read_b128 v[186:189], v133 offset:36864
	ds_read_b128 v[190:193], v133 offset:37888
	ds_read_b128 v[194:197], v133 offset:38912
	ds_read_b128 v[198:201], v133 offset:39936
	s_waitcnt vmcnt(8)
	s_waitcnt lgkmcnt(0)
	s_barrier
	s_setprio 1
	v_mfma_f32_16x16x32_bf16 v[138:141], v[134:137], v[170:173], v[138:141]
	v_mfma_f32_16x16x32_bf16 v[126:129], v[146:149], v[170:173], v[126:129]
	v_mfma_f32_16x16x32_bf16 v[110:113], v[134:137], v[178:181], v[110:113]
	v_mfma_f32_16x16x32_bf16 v[106:109], v[146:149], v[178:181], v[106:109]
	v_mfma_f32_16x16x32_bf16 v[94:97], v[134:137], v[186:189], v[94:97]
	v_mfma_f32_16x16x32_bf16 v[90:93], v[146:149], v[186:189], v[90:93]
	v_mfma_f32_16x16x32_bf16 v[78:81], v[134:137], v[194:197], v[78:81]
	v_mfma_f32_16x16x32_bf16 v[74:77], v[146:149], v[194:197], v[74:77]
	v_mfma_f32_16x16x32_bf16 v[138:141], v[142:145], v[174:177], v[138:141]
	v_mfma_f32_16x16x32_bf16 v[126:129], v[150:153], v[174:177], v[126:129]
	v_mfma_f32_16x16x32_bf16 v[110:113], v[142:145], v[182:185], v[110:113]
	v_mfma_f32_16x16x32_bf16 v[106:109], v[150:153], v[182:185], v[106:109]
	v_mfma_f32_16x16x32_bf16 v[94:97], v[142:145], v[190:193], v[94:97]
	v_mfma_f32_16x16x32_bf16 v[90:93], v[150:153], v[190:193], v[90:93]
	v_mfma_f32_16x16x32_bf16 v[78:81], v[142:145], v[198:201], v[78:81]
	v_mfma_f32_16x16x32_bf16 v[74:77], v[150:153], v[198:201], v[74:77]
	s_setprio 0
	s_setprio 1
	v_mfma_f32_16x16x32_bf16 v[118:121], v[154:157], v[170:173], v[118:121]
	v_mfma_f32_16x16x32_bf16 v[114:117], v[162:165], v[170:173], v[114:117]
	v_mfma_f32_16x16x32_bf16 v[102:105], v[154:157], v[178:181], v[102:105]
	v_mfma_f32_16x16x32_bf16 v[98:101], v[162:165], v[178:181], v[98:101]
	v_mfma_f32_16x16x32_bf16 v[86:89], v[154:157], v[186:189], v[86:89]
	v_mfma_f32_16x16x32_bf16 v[82:85], v[162:165], v[186:189], v[82:85]
	v_mfma_f32_16x16x32_bf16 v[70:73], v[154:157], v[194:197], v[70:73]
	v_mfma_f32_16x16x32_bf16 v[66:69], v[162:165], v[194:197], v[66:69]
	v_mfma_f32_16x16x32_bf16 v[118:121], v[158:161], v[174:177], v[118:121]
	v_mfma_f32_16x16x32_bf16 v[114:117], v[166:169], v[174:177], v[114:117]
	v_mfma_f32_16x16x32_bf16 v[102:105], v[158:161], v[182:185], v[102:105]
	v_mfma_f32_16x16x32_bf16 v[98:101], v[166:169], v[182:185], v[98:101]
	v_mfma_f32_16x16x32_bf16 v[86:89], v[158:161], v[190:193], v[86:89]
	v_mfma_f32_16x16x32_bf16 v[82:85], v[166:169], v[190:193], v[82:85]
	v_mfma_f32_16x16x32_bf16 v[70:73], v[158:161], v[198:201], v[70:73]
	v_mfma_f32_16x16x32_bf16 v[66:69], v[166:169], v[198:201], v[66:69]
	s_barrier
	s_setprio 0
	ds_read_b128 v[170:173], v133 offset:49152
	ds_read_b128 v[174:177], v133 offset:50176
	s_or_b32 s63, s62, 0x80
	s_mov_b32 m0, s43
	s_nop 0
	buffer_load_dwordx4 v130, s[8:11], s63 offen lds
	ds_read_b128 v[178:181], v133 offset:51200
	ds_read_b128 v[182:185], v133 offset:52224
	s_add_i32 s62, s62, 0x40080
	s_mov_b32 m0, s44
	s_nop 0
	buffer_load_dwordx4 v131, s[8:11], s63 offen lds
	ds_read_b128 v[186:189], v133 offset:53248
	ds_read_b128 v[190:193], v133 offset:54272
	s_nop 0
	s_mov_b32 m0, s47
	s_nop 0
	buffer_load_dwordx4 v130, s[8:11], s62 offen lds
	ds_read_b128 v[194:197], v133 offset:55296
	ds_read_b128 v[198:201], v133 offset:56320
	s_nop 0
	s_mov_b32 m0, s48
	s_nop 0
	buffer_load_dwordx4 v131, s[8:11], s62 offen lds
	s_nop 0
	s_mov_b32 m0, s45
	s_nop 0
	buffer_load_dwordx4 v130, s[12:15], s61 offen lds
	s_nop 0
	s_mov_b32 m0, s46
	s_nop 0
	buffer_load_dwordx4 v131, s[12:15], s61 offen lds
	s_waitcnt vmcnt(8)
	s_waitcnt lgkmcnt(0)
	s_barrier
	s_setprio 1
	v_mfma_f32_16x16x32_bf16 v[62:65], v[134:137], v[170:173], v[62:65]
	v_mfma_f32_16x16x32_bf16 v[58:61], v[146:149], v[170:173], v[58:61]
	v_mfma_f32_16x16x32_bf16 v[46:49], v[134:137], v[178:181], v[46:49]
	v_mfma_f32_16x16x32_bf16 v[42:45], v[146:149], v[178:181], v[42:45]
	v_mfma_f32_16x16x32_bf16 v[30:33], v[134:137], v[186:189], v[30:33]
	v_mfma_f32_16x16x32_bf16 v[26:29], v[146:149], v[186:189], v[26:29]
	v_mfma_f32_16x16x32_bf16 v[14:17], v[134:137], v[194:197], v[14:17]
	v_mfma_f32_16x16x32_bf16 v[10:13], v[146:149], v[194:197], v[10:13]
	v_mfma_f32_16x16x32_bf16 v[62:65], v[142:145], v[174:177], v[62:65]
	v_mfma_f32_16x16x32_bf16 v[58:61], v[150:153], v[174:177], v[58:61]
	v_mfma_f32_16x16x32_bf16 v[46:49], v[142:145], v[182:185], v[46:49]
	v_mfma_f32_16x16x32_bf16 v[42:45], v[150:153], v[182:185], v[42:45]
	v_mfma_f32_16x16x32_bf16 v[30:33], v[142:145], v[190:193], v[30:33]
	v_mfma_f32_16x16x32_bf16 v[26:29], v[150:153], v[190:193], v[26:29]
	v_mfma_f32_16x16x32_bf16 v[14:17], v[142:145], v[198:201], v[14:17]
	v_mfma_f32_16x16x32_bf16 v[10:13], v[150:153], v[198:201], v[10:13]
	s_setprio 0
	s_setprio 1
	v_mfma_f32_16x16x32_bf16 v[54:57], v[154:157], v[170:173], v[54:57]
	v_mfma_f32_16x16x32_bf16 v[50:53], v[162:165], v[170:173], v[50:53]
	v_mfma_f32_16x16x32_bf16 v[38:41], v[154:157], v[178:181], v[38:41]
	v_mfma_f32_16x16x32_bf16 v[34:37], v[162:165], v[178:181], v[34:37]
	v_mfma_f32_16x16x32_bf16 v[22:25], v[154:157], v[186:189], v[22:25]
	v_mfma_f32_16x16x32_bf16 v[18:21], v[162:165], v[186:189], v[18:21]
	v_mfma_f32_16x16x32_bf16 v[6:9], v[154:157], v[194:197], v[6:9]
	v_mfma_f32_16x16x32_bf16 v[2:5], v[162:165], v[194:197], v[2:5]
	v_mfma_f32_16x16x32_bf16 v[54:57], v[158:161], v[174:177], v[54:57]
	v_mfma_f32_16x16x32_bf16 v[50:53], v[166:169], v[174:177], v[50:53]
	v_mfma_f32_16x16x32_bf16 v[38:41], v[158:161], v[182:185], v[38:41]
	v_mfma_f32_16x16x32_bf16 v[34:37], v[166:169], v[182:185], v[34:37]
	v_mfma_f32_16x16x32_bf16 v[22:25], v[158:161], v[190:193], v[22:25]
	v_mfma_f32_16x16x32_bf16 v[18:21], v[166:169], v[190:193], v[18:21]
	v_mfma_f32_16x16x32_bf16 v[6:9], v[158:161], v[198:201], v[6:9]
	v_mfma_f32_16x16x32_bf16 v[2:5], v[166:169], v[198:201], v[2:5]
	s_barrier
	s_setprio 0
	s_add_i32 s59, s59, 2
	s_addk_i32 s60, 0x100
	s_cmp_gt_u32 s59, 13
	s_cbranch_scc0 .LBB0_223
	s_andn2_b64 vcc, exec, s[6:7]
	s_cbranch_vccnz .LBB0_215
	v_mov_b32_e32 v2, 0
	s_mov_b32 s18, s52
	s_mov_b32 s29, s53
	s_mov_b32 s34, s3
	s_mov_b32 s39, s2
	s_mov_b32 s51, s54
	v_mov_b32_e32 v3, v2
	v_mov_b32_e32 v4, v2
	v_mov_b32_e32 v5, v2
	v_mov_b32_e32 v6, v2
	v_mov_b32_e32 v7, v2
	v_mov_b32_e32 v8, v2
	v_mov_b32_e32 v9, v2
	v_mov_b32_e32 v18, v2
	v_mov_b32_e32 v19, v2
	v_mov_b32_e32 v20, v2
	v_mov_b32_e32 v21, v2
	v_mov_b32_e32 v22, v2
	v_mov_b32_e32 v23, v2
	v_mov_b32_e32 v24, v2
	v_mov_b32_e32 v25, v2
	v_mov_b32_e32 v34, v2
	v_mov_b32_e32 v35, v2
	v_mov_b32_e32 v36, v2
	v_mov_b32_e32 v37, v2
	v_mov_b32_e32 v38, v2
	v_mov_b32_e32 v39, v2
	v_mov_b32_e32 v40, v2
	v_mov_b32_e32 v41, v2
	v_mov_b32_e32 v50, v2
	v_mov_b32_e32 v51, v2
	v_mov_b32_e32 v52, v2
	v_mov_b32_e32 v53, v2
	v_mov_b32_e32 v54, v2
	v_mov_b32_e32 v55, v2
	v_mov_b32_e32 v56, v2
	v_mov_b32_e32 v57, v2
	v_mov_b32_e32 v10, v2
	v_mov_b32_e32 v11, v2
	v_mov_b32_e32 v12, v2
	v_mov_b32_e32 v13, v2
	v_mov_b32_e32 v14, v2
	v_mov_b32_e32 v15, v2
	v_mov_b32_e32 v16, v2
	v_mov_b32_e32 v17, v2
	v_mov_b32_e32 v26, v2
	v_mov_b32_e32 v27, v2
	v_mov_b32_e32 v28, v2
	v_mov_b32_e32 v29, v2
	v_mov_b32_e32 v30, v2
	v_mov_b32_e32 v31, v2
	v_mov_b32_e32 v32, v2
	v_mov_b32_e32 v33, v2
	v_mov_b32_e32 v42, v2
	v_mov_b32_e32 v43, v2
	v_mov_b32_e32 v44, v2
	v_mov_b32_e32 v45, v2
	v_mov_b32_e32 v46, v2
	v_mov_b32_e32 v47, v2
	v_mov_b32_e32 v48, v2
	v_mov_b32_e32 v49, v2
	v_mov_b32_e32 v58, v2
	v_mov_b32_e32 v59, v2
	v_mov_b32_e32 v60, v2
	v_mov_b32_e32 v61, v2
	v_mov_b32_e32 v62, v2
	v_mov_b32_e32 v63, v2
	v_mov_b32_e32 v64, v2
	v_mov_b32_e32 v65, v2
	v_mov_b32_e32 v66, v2
	v_mov_b32_e32 v67, v2
	v_mov_b32_e32 v68, v2
	v_mov_b32_e32 v69, v2
	v_mov_b32_e32 v70, v2
	v_mov_b32_e32 v71, v2
	v_mov_b32_e32 v72, v2
	v_mov_b32_e32 v73, v2
	v_mov_b32_e32 v82, v2
	v_mov_b32_e32 v83, v2
	v_mov_b32_e32 v84, v2
	v_mov_b32_e32 v85, v2
	v_mov_b32_e32 v86, v2
	v_mov_b32_e32 v87, v2
	v_mov_b32_e32 v88, v2
	v_mov_b32_e32 v89, v2
	v_mov_b32_e32 v98, v2
	v_mov_b32_e32 v99, v2
	v_mov_b32_e32 v100, v2
	v_mov_b32_e32 v101, v2
	v_mov_b32_e32 v102, v2
	v_mov_b32_e32 v103, v2
	v_mov_b32_e32 v104, v2
	v_mov_b32_e32 v105, v2
	v_mov_b32_e32 v114, v2
	v_mov_b32_e32 v115, v2
	v_mov_b32_e32 v116, v2
	v_mov_b32_e32 v117, v2
	v_mov_b32_e32 v118, v2
	v_mov_b32_e32 v119, v2
	v_mov_b32_e32 v120, v2
	v_mov_b32_e32 v121, v2
	v_mov_b32_e32 v74, v2
	v_mov_b32_e32 v75, v2
	v_mov_b32_e32 v76, v2
	v_mov_b32_e32 v77, v2
	v_mov_b32_e32 v78, v2
	v_mov_b32_e32 v79, v2
	v_mov_b32_e32 v80, v2
	v_mov_b32_e32 v81, v2
	v_mov_b32_e32 v90, v2
	v_mov_b32_e32 v91, v2
	v_mov_b32_e32 v92, v2
	v_mov_b32_e32 v93, v2
	v_mov_b32_e32 v94, v2
	v_mov_b32_e32 v95, v2
	v_mov_b32_e32 v96, v2
	v_mov_b32_e32 v97, v2
	v_mov_b32_e32 v106, v2
	v_mov_b32_e32 v107, v2
	v_mov_b32_e32 v108, v2
	v_mov_b32_e32 v109, v2
	v_mov_b32_e32 v110, v2
	v_mov_b32_e32 v111, v2
	v_mov_b32_e32 v112, v2
	v_mov_b32_e32 v113, v2
	v_mov_b32_e32 v126, v2
	v_mov_b32_e32 v127, v2
	v_mov_b32_e32 v128, v2
	v_mov_b32_e32 v129, v2
	v_mov_b32_e32 v138, v2
	v_mov_b32_e32 v139, v2
	v_mov_b32_e32 v140, v2
	v_mov_b32_e32 v141, v2
	s_branch .LBB0_215

.LBB0_353:
	ds_read_b128 v[136:139], v153
	ds_read_b128 v[140:143], v153 offset:1024
	ds_read_b128 v[158:161], v153 offset:2048
	ds_read_b128 v[162:165], v153 offset:3072
	ds_read_b128 v[166:169], v154
	ds_read_b128 v[170:173], v154 offset:1024
	ds_read_b128 v[174:177], v154 offset:2048
	ds_read_b128 v[178:181], v154 offset:3072
	s_add_i32 s66, s63, 0xfffe0080
	s_cmp_eq_u32 s65, 4
	s_cselect_b32 s68, s1, s66
	s_cselect_b32 s67, s62, s64
	s_or_b32 s66, s68, 0x80
	s_mov_b32 m0, s48
	s_nop 0
	buffer_load_dwordx4 v147, s[12:15], s63 offen lds
	s_nop 0
	s_mov_b32 m0, s49
	s_nop 0
	buffer_load_dwordx4 v148, s[12:15], s63 offen lds
	ds_read_b128 v[182:185], v155
	ds_read_b128 v[186:189], v155 offset:1024
	ds_read_b128 v[190:193], v155 offset:2048
	ds_read_b128 v[194:197], v155 offset:3072
	ds_read_b128 v[198:201], v155 offset:4096
	ds_read_b128 v[202:205], v155 offset:5120
	ds_read_b128 v[206:209], v155 offset:6144
	ds_read_b128 v[210:213], v155 offset:7168
	s_waitcnt vmcnt(8)
	s_waitcnt lgkmcnt(0)
	s_barrier
	s_setprio 1
	v_mfma_i32_16x16x64_i8 v[126:129], v[136:139], v[182:185], v[126:129]
	v_mfma_i32_16x16x64_i8 v[122:125], v[158:161], v[182:185], v[122:125]
	v_mfma_i32_16x16x64_i8 v[118:121], v[136:139], v[190:193], v[118:121]
	v_mfma_i32_16x16x64_i8 v[114:117], v[158:161], v[190:193], v[114:117]
	v_mfma_i32_16x16x64_i8 v[110:113], v[136:139], v[198:201], v[110:113]
	v_mfma_i32_16x16x64_i8 v[106:109], v[158:161], v[198:201], v[106:109]
	v_mfma_i32_16x16x64_i8 v[102:105], v[136:139], v[206:209], v[102:105]
	v_mfma_i32_16x16x64_i8 v[98:101], v[158:161], v[206:209], v[98:101]
	v_mfma_i32_16x16x64_i8 v[126:129], v[140:143], v[186:189], v[126:129]
	v_mfma_i32_16x16x64_i8 v[122:125], v[162:165], v[186:189], v[122:125]
	v_mfma_i32_16x16x64_i8 v[118:121], v[140:143], v[194:197], v[118:121]
	v_mfma_i32_16x16x64_i8 v[114:117], v[162:165], v[194:197], v[114:117]
	v_mfma_i32_16x16x64_i8 v[110:113], v[140:143], v[202:205], v[110:113]
	v_mfma_i32_16x16x64_i8 v[106:109], v[162:165], v[202:205], v[106:109]
	v_mfma_i32_16x16x64_i8 v[102:105], v[140:143], v[210:213], v[102:105]
	v_mfma_i32_16x16x64_i8 v[98:101], v[162:165], v[210:213], v[98:101]
	s_setprio 0
	s_setprio 1
	v_mfma_i32_16x16x64_i8 v[94:97], v[166:169], v[182:185], v[94:97]
	v_mfma_i32_16x16x64_i8 v[90:93], v[174:177], v[182:185], v[90:93]
	v_mfma_i32_16x16x64_i8 v[86:89], v[166:169], v[190:193], v[86:89]
	v_mfma_i32_16x16x64_i8 v[82:85], v[174:177], v[190:193], v[82:85]
	v_mfma_i32_16x16x64_i8 v[78:81], v[166:169], v[198:201], v[78:81]
	v_mfma_i32_16x16x64_i8 v[74:77], v[174:177], v[198:201], v[74:77]
	v_mfma_i32_16x16x64_i8 v[70:73], v[166:169], v[206:209], v[70:73]
	v_mfma_i32_16x16x64_i8 v[66:69], v[174:177], v[206:209], v[66:69]
	v_mfma_i32_16x16x64_i8 v[94:97], v[170:173], v[186:189], v[94:97]
	v_mfma_i32_16x16x64_i8 v[90:93], v[178:181], v[186:189], v[90:93]
	v_mfma_i32_16x16x64_i8 v[86:89], v[170:173], v[194:197], v[86:89]
	v_mfma_i32_16x16x64_i8 v[82:85], v[178:181], v[194:197], v[82:85]
	v_mfma_i32_16x16x64_i8 v[78:81], v[170:173], v[202:205], v[78:81]
	v_mfma_i32_16x16x64_i8 v[74:77], v[178:181], v[202:205], v[74:77]
	v_mfma_i32_16x16x64_i8 v[70:73], v[170:173], v[210:213], v[70:73]
	v_mfma_i32_16x16x64_i8 v[66:69], v[178:181], v[210:213], v[66:69]
	s_barrier
	s_setprio 0
	ds_read_b128 v[182:185], v155 offset:16384
	ds_read_b128 v[186:189], v155 offset:17408
	s_mov_b32 m0, s34
	s_nop 0
	buffer_load_dwordx4 v145, s[8:11], s67 offen lds
	ds_read_b128 v[190:193], v155 offset:18432
	ds_read_b128 v[194:197], v155 offset:19456
	s_add_i32 s69, s67, 0x20000
	s_mov_b32 m0, s35
	s_nop 0
	buffer_load_dwordx4 v146, s[8:11], s67 offen lds
	ds_read_b128 v[198:201], v155 offset:20480
	ds_read_b128 v[202:205], v155 offset:21504
	s_nop 0
	s_mov_b32 m0, s36
	s_nop 0
	buffer_load_dwordx4 v145, s[8:11], s69 offen lds
	ds_read_b128 v[206:209], v155 offset:22528
	ds_read_b128 v[210:213], v155 offset:23552
	s_nop 0
	s_mov_b32 m0, s37
	s_nop 0
	buffer_load_dwordx4 v146, s[8:11], s69 offen lds
	s_nop 0
	s_mov_b32 m0, s33
	s_nop 0
	buffer_load_dwordx4 v147, s[12:15], s68 offen lds
	s_nop 0
	s_mov_b32 m0, s2
	s_nop 0
	buffer_load_dwordx4 v148, s[12:15], s68 offen lds
	s_waitcnt vmcnt(8)
	s_waitcnt lgkmcnt(0)
	s_barrier
	s_setprio 1
	v_mfma_i32_16x16x64_i8 v[62:65], v[136:139], v[182:185], v[62:65]
	v_mfma_i32_16x16x64_i8 v[58:61], v[158:161], v[182:185], v[58:61]
	v_mfma_i32_16x16x64_i8 v[54:57], v[136:139], v[190:193], v[54:57]
	v_mfma_i32_16x16x64_i8 v[50:53], v[158:161], v[190:193], v[50:53]
	v_mfma_i32_16x16x64_i8 v[46:49], v[136:139], v[198:201], v[46:49]
	v_mfma_i32_16x16x64_i8 v[42:45], v[158:161], v[198:201], v[42:45]
	v_mfma_i32_16x16x64_i8 v[38:41], v[136:139], v[206:209], v[38:41]
	v_mfma_i32_16x16x64_i8 v[34:37], v[158:161], v[206:209], v[34:37]
	v_mfma_i32_16x16x64_i8 v[62:65], v[140:143], v[186:189], v[62:65]
	v_mfma_i32_16x16x64_i8 v[58:61], v[162:165], v[186:189], v[58:61]
	v_mfma_i32_16x16x64_i8 v[54:57], v[140:143], v[194:197], v[54:57]
	v_mfma_i32_16x16x64_i8 v[50:53], v[162:165], v[194:197], v[50:53]
	v_mfma_i32_16x16x64_i8 v[46:49], v[140:143], v[202:205], v[46:49]
	v_mfma_i32_16x16x64_i8 v[42:45], v[162:165], v[202:205], v[42:45]
	v_mfma_i32_16x16x64_i8 v[38:41], v[140:143], v[210:213], v[38:41]
	v_mfma_i32_16x16x64_i8 v[34:37], v[162:165], v[210:213], v[34:37]
	s_setprio 0
	s_setprio 1
	v_mfma_i32_16x16x64_i8 v[30:33], v[166:169], v[182:185], v[30:33]
	v_mfma_i32_16x16x64_i8 v[26:29], v[174:177], v[182:185], v[26:29]
	v_mfma_i32_16x16x64_i8 v[22:25], v[166:169], v[190:193], v[22:25]
	v_mfma_i32_16x16x64_i8 v[18:21], v[174:177], v[190:193], v[18:21]
	v_mfma_i32_16x16x64_i8 v[14:17], v[166:169], v[198:201], v[14:17]
	v_mfma_i32_16x16x64_i8 v[10:13], v[174:177], v[198:201], v[10:13]
	v_mfma_i32_16x16x64_i8 v[6:9], v[166:169], v[206:209], v[6:9]
	v_mfma_i32_16x16x64_i8 v[2:5], v[174:177], v[206:209], v[2:5]
	v_mfma_i32_16x16x64_i8 v[30:33], v[170:173], v[186:189], v[30:33]
	v_mfma_i32_16x16x64_i8 v[26:29], v[178:181], v[186:189], v[26:29]
	v_mfma_i32_16x16x64_i8 v[22:25], v[170:173], v[194:197], v[22:25]
	v_mfma_i32_16x16x64_i8 v[18:21], v[178:181], v[194:197], v[18:21]
	v_mfma_i32_16x16x64_i8 v[14:17], v[170:173], v[202:205], v[14:17]
	v_mfma_i32_16x16x64_i8 v[10:13], v[178:181], v[202:205], v[10:13]
	v_mfma_i32_16x16x64_i8 v[6:9], v[170:173], v[210:213], v[6:9]
	v_mfma_i32_16x16x64_i8 v[2:5], v[178:181], v[210:213], v[2:5]
	s_barrier
	s_setprio 0
	ds_read_b128 v[136:139], v156
	ds_read_b128 v[140:143], v156 offset:1024
	ds_read_b128 v[158:161], v156 offset:2048
	ds_read_b128 v[162:165], v156 offset:3072
	ds_read_b128 v[166:169], v157
	ds_read_b128 v[170:173], v157 offset:1024
	ds_read_b128 v[174:177], v157 offset:2048
	ds_read_b128 v[178:181], v157 offset:3072
	s_add_i32 s68, s68, 0x20000
	s_mov_b32 m0, s3
	s_nop 0
	buffer_load_dwordx4 v147, s[12:15], s68 offen lds
	s_nop 0
	s_mov_b32 m0, s38
	s_nop 0
	buffer_load_dwordx4 v148, s[12:15], s68 offen lds
	ds_read_b128 v[182:185], v155 offset:32768
	ds_read_b128 v[186:189], v155 offset:33792
	ds_read_b128 v[190:193], v155 offset:34816
	ds_read_b128 v[194:197], v155 offset:35840
	ds_read_b128 v[198:201], v155 offset:36864
	ds_read_b128 v[202:205], v155 offset:37888
	ds_read_b128 v[206:209], v155 offset:38912
	ds_read_b128 v[210:213], v155 offset:39936
	s_waitcnt vmcnt(8)
	s_waitcnt lgkmcnt(0)
	s_barrier
	s_setprio 1
	v_mfma_i32_16x16x64_i8 v[126:129], v[136:139], v[182:185], v[126:129]
	v_mfma_i32_16x16x64_i8 v[122:125], v[158:161], v[182:185], v[122:125]
	v_mfma_i32_16x16x64_i8 v[118:121], v[136:139], v[190:193], v[118:121]
	v_mfma_i32_16x16x64_i8 v[114:117], v[158:161], v[190:193], v[114:117]
	v_mfma_i32_16x16x64_i8 v[110:113], v[136:139], v[198:201], v[110:113]
	v_mfma_i32_16x16x64_i8 v[106:109], v[158:161], v[198:201], v[106:109]
	v_mfma_i32_16x16x64_i8 v[102:105], v[136:139], v[206:209], v[102:105]
	v_mfma_i32_16x16x64_i8 v[98:101], v[158:161], v[206:209], v[98:101]
	v_mfma_i32_16x16x64_i8 v[126:129], v[140:143], v[186:189], v[126:129]
	v_mfma_i32_16x16x64_i8 v[122:125], v[162:165], v[186:189], v[122:125]
	v_mfma_i32_16x16x64_i8 v[118:121], v[140:143], v[194:197], v[118:121]
	v_mfma_i32_16x16x64_i8 v[114:117], v[162:165], v[194:197], v[114:117]
	v_mfma_i32_16x16x64_i8 v[110:113], v[140:143], v[202:205], v[110:113]
	v_mfma_i32_16x16x64_i8 v[106:109], v[162:165], v[202:205], v[106:109]
	v_mfma_i32_16x16x64_i8 v[102:105], v[140:143], v[210:213], v[102:105]
	v_mfma_i32_16x16x64_i8 v[98:101], v[162:165], v[210:213], v[98:101]
	s_setprio 0
	s_setprio 1
	v_mfma_i32_16x16x64_i8 v[94:97], v[166:169], v[182:185], v[94:97]
	v_mfma_i32_16x16x64_i8 v[90:93], v[174:177], v[182:185], v[90:93]
	v_mfma_i32_16x16x64_i8 v[86:89], v[166:169], v[190:193], v[86:89]
	v_mfma_i32_16x16x64_i8 v[82:85], v[174:177], v[190:193], v[82:85]
	v_mfma_i32_16x16x64_i8 v[78:81], v[166:169], v[198:201], v[78:81]
	v_mfma_i32_16x16x64_i8 v[74:77], v[174:177], v[198:201], v[74:77]
	v_mfma_i32_16x16x64_i8 v[70:73], v[166:169], v[206:209], v[70:73]
	v_mfma_i32_16x16x64_i8 v[66:69], v[174:177], v[206:209], v[66:69]
	v_mfma_i32_16x16x64_i8 v[94:97], v[170:173], v[186:189], v[94:97]
	v_mfma_i32_16x16x64_i8 v[90:93], v[178:181], v[186:189], v[90:93]
	v_mfma_i32_16x16x64_i8 v[86:89], v[170:173], v[194:197], v[86:89]
	v_mfma_i32_16x16x64_i8 v[82:85], v[178:181], v[194:197], v[82:85]
	v_mfma_i32_16x16x64_i8 v[78:81], v[170:173], v[202:205], v[78:81]
	v_mfma_i32_16x16x64_i8 v[74:77], v[178:181], v[202:205], v[74:77]
	v_mfma_i32_16x16x64_i8 v[70:73], v[170:173], v[210:213], v[70:73]
	v_mfma_i32_16x16x64_i8 v[66:69], v[178:181], v[210:213], v[66:69]
	s_barrier
	s_setprio 0
	ds_read_b128 v[182:185], v155 offset:49152
	ds_read_b128 v[186:189], v155 offset:50176
	s_or_b32 s68, s67, 0x80
	s_mov_b32 m0, s41
	s_nop 0
	buffer_load_dwordx4 v145, s[8:11], s68 offen lds
	ds_read_b128 v[190:193], v155 offset:51200
	ds_read_b128 v[194:197], v155 offset:52224
	s_add_i32 s67, s67, 0x20080
	s_mov_b32 m0, s42
	s_nop 0
	buffer_load_dwordx4 v146, s[8:11], s68 offen lds
	ds_read_b128 v[198:201], v155 offset:53248
	ds_read_b128 v[202:205], v155 offset:54272
	s_nop 0
	s_mov_b32 m0, s45
	s_nop 0
	buffer_load_dwordx4 v145, s[8:11], s67 offen lds
	ds_read_b128 v[206:209], v155 offset:55296
	ds_read_b128 v[210:213], v155 offset:56320
	s_nop 0
	s_mov_b32 m0, s46
	s_nop 0
	buffer_load_dwordx4 v146, s[8:11], s67 offen lds
	s_nop 0
	s_mov_b32 m0, s43
	s_nop 0
	buffer_load_dwordx4 v147, s[12:15], s66 offen lds
	s_nop 0
	s_mov_b32 m0, s44
	s_nop 0
	buffer_load_dwordx4 v148, s[12:15], s66 offen lds
	s_waitcnt vmcnt(8)
	s_waitcnt lgkmcnt(0)
	s_barrier
	s_setprio 1
	v_mfma_i32_16x16x64_i8 v[62:65], v[136:139], v[182:185], v[62:65]
	v_mfma_i32_16x16x64_i8 v[58:61], v[158:161], v[182:185], v[58:61]
	v_mfma_i32_16x16x64_i8 v[54:57], v[136:139], v[190:193], v[54:57]
	v_mfma_i32_16x16x64_i8 v[50:53], v[158:161], v[190:193], v[50:53]
	v_mfma_i32_16x16x64_i8 v[46:49], v[136:139], v[198:201], v[46:49]
	v_mfma_i32_16x16x64_i8 v[42:45], v[158:161], v[198:201], v[42:45]
	v_mfma_i32_16x16x64_i8 v[38:41], v[136:139], v[206:209], v[38:41]
	v_mfma_i32_16x16x64_i8 v[34:37], v[158:161], v[206:209], v[34:37]
	v_mfma_i32_16x16x64_i8 v[62:65], v[140:143], v[186:189], v[62:65]
	v_mfma_i32_16x16x64_i8 v[58:61], v[162:165], v[186:189], v[58:61]
	v_mfma_i32_16x16x64_i8 v[54:57], v[140:143], v[194:197], v[54:57]
	v_mfma_i32_16x16x64_i8 v[50:53], v[162:165], v[194:197], v[50:53]
	v_mfma_i32_16x16x64_i8 v[46:49], v[140:143], v[202:205], v[46:49]
	v_mfma_i32_16x16x64_i8 v[42:45], v[162:165], v[202:205], v[42:45]
	v_mfma_i32_16x16x64_i8 v[38:41], v[140:143], v[210:213], v[38:41]
	v_mfma_i32_16x16x64_i8 v[34:37], v[162:165], v[210:213], v[34:37]
	s_setprio 0
	s_setprio 1
	v_mfma_i32_16x16x64_i8 v[30:33], v[166:169], v[182:185], v[30:33]
	v_mfma_i32_16x16x64_i8 v[26:29], v[174:177], v[182:185], v[26:29]
	v_mfma_i32_16x16x64_i8 v[22:25], v[166:169], v[190:193], v[22:25]
	v_mfma_i32_16x16x64_i8 v[18:21], v[174:177], v[190:193], v[18:21]
	v_mfma_i32_16x16x64_i8 v[14:17], v[166:169], v[198:201], v[14:17]
	v_mfma_i32_16x16x64_i8 v[10:13], v[174:177], v[198:201], v[10:13]
	v_mfma_i32_16x16x64_i8 v[6:9], v[166:169], v[206:209], v[6:9]
	v_mfma_i32_16x16x64_i8 v[2:5], v[174:177], v[206:209], v[2:5]
	v_mfma_i32_16x16x64_i8 v[30:33], v[170:173], v[186:189], v[30:33]
	v_mfma_i32_16x16x64_i8 v[26:29], v[178:181], v[186:189], v[26:29]
	v_mfma_i32_16x16x64_i8 v[22:25], v[170:173], v[194:197], v[22:25]
	v_mfma_i32_16x16x64_i8 v[18:21], v[178:181], v[194:197], v[18:21]
	v_mfma_i32_16x16x64_i8 v[14:17], v[170:173], v[202:205], v[14:17]
	v_mfma_i32_16x16x64_i8 v[10:13], v[178:181], v[202:205], v[10:13]
	v_mfma_i32_16x16x64_i8 v[6:9], v[170:173], v[210:213], v[6:9]
	v_mfma_i32_16x16x64_i8 v[2:5], v[178:181], v[210:213], v[2:5]
	s_barrier
	s_setprio 0
	s_add_i32 s65, s65, 2
	s_addk_i32 s63, 0x100
	s_addk_i32 s64, 0x100
	s_cmp_gt_u32 s65, 5
	s_cbranch_scc0 .LBB0_353
	s_and_b64 vcc, exec, s[24:25]
	s_cbranch_vccz .LBB0_356
	s_barrier

.LBB0_467:
	v_add_u32_e32 v147, 0x10000, v132
	ds_read_b128 v[138:141], v147
	ds_read_b128 v[142:145], v147 offset:1024
	ds_read_b128 v[148:151], v147 offset:2048
	ds_read_b128 v[152:155], v147 offset:3072
	v_add_u32_e32 v147, 0x14000, v132
	ds_read_b128 v[156:159], v147
	ds_read_b128 v[160:163], v147 offset:1024
	ds_read_b128 v[164:167], v147 offset:2048
	ds_read_b128 v[168:171], v147 offset:3072
	s_add_i32 s59, s3, s1
	s_add_i32 s58, s33, s1
	s_add_i32 s55, s59, 0x1600
	s_addk_i32 s58, 0x1600
	s_cmp_eq_u32 s1, 0
	s_cselect_b32 s60, s53, s55
	s_cselect_b32 s58, s54, s58
	s_add_i32 s55, s60, 0x80
	s_add_i32 s59, s59, 0xb1580
	s_mov_b32 m0, s46
	s_nop 0
	buffer_load_dwordx4 v130, s[12:15], s59 offen lds
	s_nop 0
	s_mov_b32 m0, s47
	s_nop 0
	buffer_load_dwordx4 v131, s[12:15], s59 offen lds
	ds_read_b128 v[172:175], v133
	ds_read_b128 v[176:179], v133 offset:1024
	ds_read_b128 v[180:183], v133 offset:2048
	ds_read_b128 v[184:187], v133 offset:3072
	ds_read_b128 v[188:191], v133 offset:4096
	ds_read_b128 v[192:195], v133 offset:5120
	ds_read_b128 v[196:199], v133 offset:6144
	ds_read_b128 v[200:203], v133 offset:7168
	s_waitcnt vmcnt(8)
	s_waitcnt lgkmcnt(0)
	s_barrier
	s_setprio 1
	v_mfma_f32_16x16x32_bf16 v[134:137], v[138:141], v[172:175], v[134:137]
	v_mfma_f32_16x16x32_bf16 v[122:125], v[148:151], v[172:175], v[122:125]
	v_mfma_f32_16x16x32_bf16 v[110:113], v[138:141], v[180:183], v[110:113]
	v_mfma_f32_16x16x32_bf16 v[106:109], v[148:151], v[180:183], v[106:109]
	v_mfma_f32_16x16x32_bf16 v[94:97], v[138:141], v[188:191], v[94:97]
	v_mfma_f32_16x16x32_bf16 v[90:93], v[148:151], v[188:191], v[90:93]
	v_mfma_f32_16x16x32_bf16 v[78:81], v[138:141], v[196:199], v[78:81]
	v_mfma_f32_16x16x32_bf16 v[74:77], v[148:151], v[196:199], v[74:77]
	v_mfma_f32_16x16x32_bf16 v[134:137], v[142:145], v[176:179], v[134:137]
	v_mfma_f32_16x16x32_bf16 v[122:125], v[152:155], v[176:179], v[122:125]
	v_mfma_f32_16x16x32_bf16 v[110:113], v[142:145], v[184:187], v[110:113]
	v_mfma_f32_16x16x32_bf16 v[106:109], v[152:155], v[184:187], v[106:109]
	v_mfma_f32_16x16x32_bf16 v[94:97], v[142:145], v[192:195], v[94:97]
	v_mfma_f32_16x16x32_bf16 v[90:93], v[152:155], v[192:195], v[90:93]
	v_mfma_f32_16x16x32_bf16 v[78:81], v[142:145], v[200:203], v[78:81]
	v_mfma_f32_16x16x32_bf16 v[74:77], v[152:155], v[200:203], v[74:77]
	s_setprio 0
	s_setprio 1
	v_mfma_f32_16x16x32_bf16 v[118:121], v[156:159], v[172:175], v[118:121]
	v_mfma_f32_16x16x32_bf16 v[114:117], v[164:167], v[172:175], v[114:117]
	v_mfma_f32_16x16x32_bf16 v[102:105], v[156:159], v[180:183], v[102:105]
	v_mfma_f32_16x16x32_bf16 v[98:101], v[164:167], v[180:183], v[98:101]
	v_mfma_f32_16x16x32_bf16 v[86:89], v[156:159], v[188:191], v[86:89]
	v_mfma_f32_16x16x32_bf16 v[82:85], v[164:167], v[188:191], v[82:85]
	v_mfma_f32_16x16x32_bf16 v[70:73], v[156:159], v[196:199], v[70:73]
	v_mfma_f32_16x16x32_bf16 v[66:69], v[164:167], v[196:199], v[66:69]
	v_mfma_f32_16x16x32_bf16 v[118:121], v[160:163], v[176:179], v[118:121]
	v_mfma_f32_16x16x32_bf16 v[114:117], v[168:171], v[176:179], v[114:117]
	v_mfma_f32_16x16x32_bf16 v[102:105], v[160:163], v[184:187], v[102:105]
	v_mfma_f32_16x16x32_bf16 v[98:101], v[168:171], v[184:187], v[98:101]
	v_mfma_f32_16x16x32_bf16 v[86:89], v[160:163], v[192:195], v[86:89]
	v_mfma_f32_16x16x32_bf16 v[82:85], v[168:171], v[192:195], v[82:85]
	v_mfma_f32_16x16x32_bf16 v[70:73], v[160:163], v[200:203], v[70:73]
	v_mfma_f32_16x16x32_bf16 v[66:69], v[168:171], v[200:203], v[66:69]
	s_barrier
	s_setprio 0
	ds_read_b128 v[172:175], v133 offset:16384
	ds_read_b128 v[176:179], v133 offset:17408
	s_mov_b32 m0, s29
	s_nop 0
	buffer_load_dwordx4 v130, s[8:11], s58 offen lds
	ds_read_b128 v[180:183], v133 offset:18432
	ds_read_b128 v[184:187], v133 offset:19456
	s_add_i32 s59, s58, 0xb0000
	s_mov_b32 m0, s34
	s_nop 0
	buffer_load_dwordx4 v131, s[8:11], s58 offen lds
	ds_read_b128 v[188:191], v133 offset:20480
	ds_read_b128 v[192:195], v133 offset:21504
	s_nop 0
	s_mov_b32 m0, s35
	s_nop 0
	buffer_load_dwordx4 v130, s[8:11], s59 offen lds
	ds_read_b128 v[196:199], v133 offset:22528
	ds_read_b128 v[200:203], v133 offset:23552
	s_nop 0
	s_mov_b32 m0, s36
	s_nop 0
	buffer_load_dwordx4 v131, s[8:11], s59 offen lds
	s_nop 0
	s_mov_b32 m0, s28
	s_nop 0
	buffer_load_dwordx4 v130, s[12:15], s60 offen lds
	s_nop 0
	s_mov_b32 m0, s37
	s_nop 0
	buffer_load_dwordx4 v131, s[12:15], s60 offen lds
	s_waitcnt vmcnt(8)
	s_waitcnt lgkmcnt(0)
	s_barrier
	s_setprio 1
	v_mfma_f32_16x16x32_bf16 v[62:65], v[138:141], v[172:175], v[62:65]
	v_mfma_f32_16x16x32_bf16 v[58:61], v[148:151], v[172:175], v[58:61]
	v_mfma_f32_16x16x32_bf16 v[46:49], v[138:141], v[180:183], v[46:49]
	v_mfma_f32_16x16x32_bf16 v[42:45], v[148:151], v[180:183], v[42:45]
	v_mfma_f32_16x16x32_bf16 v[30:33], v[138:141], v[188:191], v[30:33]
	v_mfma_f32_16x16x32_bf16 v[26:29], v[148:151], v[188:191], v[26:29]
	v_mfma_f32_16x16x32_bf16 v[14:17], v[138:141], v[196:199], v[14:17]
	v_mfma_f32_16x16x32_bf16 v[10:13], v[148:151], v[196:199], v[10:13]
	v_mfma_f32_16x16x32_bf16 v[62:65], v[142:145], v[176:179], v[62:65]
	v_mfma_f32_16x16x32_bf16 v[58:61], v[152:155], v[176:179], v[58:61]
	v_mfma_f32_16x16x32_bf16 v[46:49], v[142:145], v[184:187], v[46:49]
	v_mfma_f32_16x16x32_bf16 v[42:45], v[152:155], v[184:187], v[42:45]
	v_mfma_f32_16x16x32_bf16 v[30:33], v[142:145], v[192:195], v[30:33]
	v_mfma_f32_16x16x32_bf16 v[26:29], v[152:155], v[192:195], v[26:29]
	v_mfma_f32_16x16x32_bf16 v[14:17], v[142:145], v[200:203], v[14:17]
	v_mfma_f32_16x16x32_bf16 v[10:13], v[152:155], v[200:203], v[10:13]
	s_setprio 0
	s_setprio 1
	v_mfma_f32_16x16x32_bf16 v[54:57], v[156:159], v[172:175], v[54:57]
	v_mfma_f32_16x16x32_bf16 v[50:53], v[164:167], v[172:175], v[50:53]
	v_mfma_f32_16x16x32_bf16 v[38:41], v[156:159], v[180:183], v[38:41]
	v_mfma_f32_16x16x32_bf16 v[34:37], v[164:167], v[180:183], v[34:37]
	v_mfma_f32_16x16x32_bf16 v[22:25], v[156:159], v[188:191], v[22:25]
	v_mfma_f32_16x16x32_bf16 v[18:21], v[164:167], v[188:191], v[18:21]
	v_mfma_f32_16x16x32_bf16 v[6:9], v[156:159], v[196:199], v[6:9]
	v_mfma_f32_16x16x32_bf16 v[2:5], v[164:167], v[196:199], v[2:5]
	v_mfma_f32_16x16x32_bf16 v[54:57], v[160:163], v[176:179], v[54:57]
	v_mfma_f32_16x16x32_bf16 v[50:53], v[168:171], v[176:179], v[50:53]
	v_mfma_f32_16x16x32_bf16 v[38:41], v[160:163], v[184:187], v[38:41]
	v_mfma_f32_16x16x32_bf16 v[34:37], v[168:171], v[184:187], v[34:37]
	v_mfma_f32_16x16x32_bf16 v[22:25], v[160:163], v[192:195], v[22:25]
	v_mfma_f32_16x16x32_bf16 v[18:21], v[168:171], v[192:195], v[18:21]
	v_mfma_f32_16x16x32_bf16 v[6:9], v[160:163], v[200:203], v[6:9]
	v_mfma_f32_16x16x32_bf16 v[2:5], v[168:171], v[200:203], v[2:5]
	s_barrier
	s_setprio 0
	v_add_u32_e32 v147, 0x18000, v132
	ds_read_b128 v[138:141], v147
	ds_read_b128 v[142:145], v147 offset:1024
	ds_read_b128 v[148:151], v147 offset:2048
	ds_read_b128 v[152:155], v147 offset:3072
	v_add_u32_e32 v147, 0x1c000, v132
	ds_read_b128 v[156:159], v147
	ds_read_b128 v[160:163], v147 offset:1024
	ds_read_b128 v[164:167], v147 offset:2048
	ds_read_b128 v[168:171], v147 offset:3072
	s_add_i32 s59, s60, 0xb0000
	s_mov_b32 m0, s38
	s_nop 0
	buffer_load_dwordx4 v130, s[12:15], s59 offen lds
	s_nop 0
	s_mov_b32 m0, s39
	s_nop 0
	buffer_load_dwordx4 v131, s[12:15], s59 offen lds
	ds_read_b128 v[172:175], v133 offset:32768
	ds_read_b128 v[176:179], v133 offset:33792
	ds_read_b128 v[180:183], v133 offset:34816
	ds_read_b128 v[184:187], v133 offset:35840
	ds_read_b128 v[188:191], v133 offset:36864
	ds_read_b128 v[192:195], v133 offset:37888
	ds_read_b128 v[196:199], v133 offset:38912
	ds_read_b128 v[200:203], v133 offset:39936
	s_waitcnt vmcnt(8)
	s_waitcnt lgkmcnt(0)
	s_barrier
	s_setprio 1
	v_mfma_f32_16x16x32_bf16 v[134:137], v[138:141], v[172:175], v[134:137]
	v_mfma_f32_16x16x32_bf16 v[122:125], v[148:151], v[172:175], v[122:125]
	v_mfma_f32_16x16x32_bf16 v[110:113], v[138:141], v[180:183], v[110:113]
	v_mfma_f32_16x16x32_bf16 v[106:109], v[148:151], v[180:183], v[106:109]
	v_mfma_f32_16x16x32_bf16 v[94:97], v[138:141], v[188:191], v[94:97]
	v_mfma_f32_16x16x32_bf16 v[90:93], v[148:151], v[188:191], v[90:93]
	v_mfma_f32_16x16x32_bf16 v[78:81], v[138:141], v[196:199], v[78:81]
	v_mfma_f32_16x16x32_bf16 v[74:77], v[148:151], v[196:199], v[74:77]
	v_mfma_f32_16x16x32_bf16 v[134:137], v[142:145], v[176:179], v[134:137]
	v_mfma_f32_16x16x32_bf16 v[122:125], v[152:155], v[176:179], v[122:125]
	v_mfma_f32_16x16x32_bf16 v[110:113], v[142:145], v[184:187], v[110:113]
	v_mfma_f32_16x16x32_bf16 v[106:109], v[152:155], v[184:187], v[106:109]
	v_mfma_f32_16x16x32_bf16 v[94:97], v[142:145], v[192:195], v[94:97]
	v_mfma_f32_16x16x32_bf16 v[90:93], v[152:155], v[192:195], v[90:93]
	v_mfma_f32_16x16x32_bf16 v[78:81], v[142:145], v[200:203], v[78:81]
	v_mfma_f32_16x16x32_bf16 v[74:77], v[152:155], v[200:203], v[74:77]
	s_setprio 0
	s_setprio 1
	v_mfma_f32_16x16x32_bf16 v[118:121], v[156:159], v[172:175], v[118:121]
	v_mfma_f32_16x16x32_bf16 v[114:117], v[164:167], v[172:175], v[114:117]
	v_mfma_f32_16x16x32_bf16 v[102:105], v[156:159], v[180:183], v[102:105]
	v_mfma_f32_16x16x32_bf16 v[98:101], v[164:167], v[180:183], v[98:101]
	v_mfma_f32_16x16x32_bf16 v[86:89], v[156:159], v[188:191], v[86:89]
	v_mfma_f32_16x16x32_bf16 v[82:85], v[164:167], v[188:191], v[82:85]
	v_mfma_f32_16x16x32_bf16 v[70:73], v[156:159], v[196:199], v[70:73]
	v_mfma_f32_16x16x32_bf16 v[66:69], v[164:167], v[196:199], v[66:69]
	v_mfma_f32_16x16x32_bf16 v[118:121], v[160:163], v[176:179], v[118:121]
	v_mfma_f32_16x16x32_bf16 v[114:117], v[168:171], v[176:179], v[114:117]
	v_mfma_f32_16x16x32_bf16 v[102:105], v[160:163], v[184:187], v[102:105]
	v_mfma_f32_16x16x32_bf16 v[98:101], v[168:171], v[184:187], v[98:101]
	v_mfma_f32_16x16x32_bf16 v[86:89], v[160:163], v[192:195], v[86:89]
	v_mfma_f32_16x16x32_bf16 v[82:85], v[168:171], v[192:195], v[82:85]
	v_mfma_f32_16x16x32_bf16 v[70:73], v[160:163], v[200:203], v[70:73]
	v_mfma_f32_16x16x32_bf16 v[66:69], v[168:171], v[200:203], v[66:69]
	s_barrier
	s_setprio 0
	ds_read_b128 v[172:175], v133 offset:49152
	ds_read_b128 v[176:179], v133 offset:50176
	s_add_i32 s59, s58, 0x80
	s_mov_b32 m0, s40
	s_nop 0
	buffer_load_dwordx4 v130, s[8:11], s59 offen lds
	ds_read_b128 v[180:183], v133 offset:51200
	ds_read_b128 v[184:187], v133 offset:52224
	s_add_i32 s58, s58, 0xb0080
	s_mov_b32 m0, s41
	s_nop 0
	buffer_load_dwordx4 v131, s[8:11], s59 offen lds
	ds_read_b128 v[188:191], v133 offset:53248
	ds_read_b128 v[192:195], v133 offset:54272
	s_nop 0
	s_mov_b32 m0, s44
	s_nop 0
	buffer_load_dwordx4 v130, s[8:11], s58 offen lds
	ds_read_b128 v[196:199], v133 offset:55296
	ds_read_b128 v[200:203], v133 offset:56320
	s_nop 0
	s_mov_b32 m0, s45
	s_nop 0
	buffer_load_dwordx4 v131, s[8:11], s58 offen lds
	s_nop 0
	s_mov_b32 m0, s42
	s_nop 0
	buffer_load_dwordx4 v130, s[12:15], s55 offen lds
	s_nop 0
	s_mov_b32 m0, s43
	s_nop 0
	buffer_load_dwordx4 v131, s[12:15], s55 offen lds
	s_waitcnt vmcnt(8)
	s_waitcnt lgkmcnt(0)
	s_barrier
	s_setprio 1
	v_mfma_f32_16x16x32_bf16 v[62:65], v[138:141], v[172:175], v[62:65]
	v_mfma_f32_16x16x32_bf16 v[58:61], v[148:151], v[172:175], v[58:61]
	v_mfma_f32_16x16x32_bf16 v[46:49], v[138:141], v[180:183], v[46:49]
	v_mfma_f32_16x16x32_bf16 v[42:45], v[148:151], v[180:183], v[42:45]
	v_mfma_f32_16x16x32_bf16 v[30:33], v[138:141], v[188:191], v[30:33]
	v_mfma_f32_16x16x32_bf16 v[26:29], v[148:151], v[188:191], v[26:29]
	v_mfma_f32_16x16x32_bf16 v[14:17], v[138:141], v[196:199], v[14:17]
	v_mfma_f32_16x16x32_bf16 v[10:13], v[148:151], v[196:199], v[10:13]
	v_mfma_f32_16x16x32_bf16 v[62:65], v[142:145], v[176:179], v[62:65]
	v_mfma_f32_16x16x32_bf16 v[58:61], v[152:155], v[176:179], v[58:61]
	v_mfma_f32_16x16x32_bf16 v[46:49], v[142:145], v[184:187], v[46:49]
	v_mfma_f32_16x16x32_bf16 v[42:45], v[152:155], v[184:187], v[42:45]
	v_mfma_f32_16x16x32_bf16 v[30:33], v[142:145], v[192:195], v[30:33]
	v_mfma_f32_16x16x32_bf16 v[26:29], v[152:155], v[192:195], v[26:29]
	v_mfma_f32_16x16x32_bf16 v[14:17], v[142:145], v[200:203], v[14:17]
	v_mfma_f32_16x16x32_bf16 v[10:13], v[152:155], v[200:203], v[10:13]
	s_setprio 0
	s_setprio 1
	v_mfma_f32_16x16x32_bf16 v[54:57], v[156:159], v[172:175], v[54:57]
	v_mfma_f32_16x16x32_bf16 v[50:53], v[164:167], v[172:175], v[50:53]
	v_mfma_f32_16x16x32_bf16 v[38:41], v[156:159], v[180:183], v[38:41]
	v_mfma_f32_16x16x32_bf16 v[34:37], v[164:167], v[180:183], v[34:37]
	v_mfma_f32_16x16x32_bf16 v[22:25], v[156:159], v[188:191], v[22:25]
	v_mfma_f32_16x16x32_bf16 v[18:21], v[164:167], v[188:191], v[18:21]
	v_mfma_f32_16x16x32_bf16 v[6:9], v[156:159], v[196:199], v[6:9]
	v_mfma_f32_16x16x32_bf16 v[2:5], v[164:167], v[196:199], v[2:5]
	v_mfma_f32_16x16x32_bf16 v[54:57], v[160:163], v[176:179], v[54:57]
	v_mfma_f32_16x16x32_bf16 v[50:53], v[168:171], v[176:179], v[50:53]
	v_mfma_f32_16x16x32_bf16 v[38:41], v[160:163], v[184:187], v[38:41]
	v_mfma_f32_16x16x32_bf16 v[34:37], v[168:171], v[184:187], v[34:37]
	v_mfma_f32_16x16x32_bf16 v[22:25], v[160:163], v[192:195], v[22:25]
	v_mfma_f32_16x16x32_bf16 v[18:21], v[168:171], v[192:195], v[18:21]
	v_mfma_f32_16x16x32_bf16 v[6:9], v[160:163], v[200:203], v[6:9]
	v_mfma_f32_16x16x32_bf16 v[2:5], v[168:171], v[200:203], v[2:5]
	s_barrier
	s_setprio 0
	s_add_i32 s0, s0, 2
	s_addk_i32 s1, 0x100
	s_cmp_gt_u32 s0, 41
	s_cbranch_scc0 .LBB0_467
	s_andn2_b64 vcc, exec, s[6:7]
	s_cbranch_vccnz .LBB0_455
	v_mov_b32_e32 v2, 0
	s_mov_b32 s18, s50
	s_mov_b32 s31, s51
	s_mov_b32 s33, s54
	s_mov_b32 s3, s53
	s_mov_b32 s49, s52
	v_mov_b32_e32 v3, v2
	v_mov_b32_e32 v4, v2
	v_mov_b32_e32 v5, v2
	v_mov_b32_e32 v6, v2
	v_mov_b32_e32 v7, v2
	v_mov_b32_e32 v8, v2
	v_mov_b32_e32 v9, v2
	v_mov_b32_e32 v18, v2
	v_mov_b32_e32 v19, v2
	v_mov_b32_e32 v20, v2
	v_mov_b32_e32 v21, v2
	v_mov_b32_e32 v22, v2
	v_mov_b32_e32 v23, v2
	v_mov_b32_e32 v24, v2
	v_mov_b32_e32 v25, v2
	v_mov_b32_e32 v34, v2
	v_mov_b32_e32 v35, v2
	v_mov_b32_e32 v36, v2
	v_mov_b32_e32 v37, v2
	v_mov_b32_e32 v38, v2
	v_mov_b32_e32 v39, v2
	v_mov_b32_e32 v40, v2
	v_mov_b32_e32 v41, v2
	v_mov_b32_e32 v50, v2
	v_mov_b32_e32 v51, v2
	v_mov_b32_e32 v52, v2
	v_mov_b32_e32 v53, v2
	v_mov_b32_e32 v54, v2
	v_mov_b32_e32 v55, v2
	v_mov_b32_e32 v56, v2
	v_mov_b32_e32 v57, v2
	v_mov_b32_e32 v10, v2
	v_mov_b32_e32 v11, v2
	v_mov_b32_e32 v12, v2
	v_mov_b32_e32 v13, v2
	v_mov_b32_e32 v14, v2
	v_mov_b32_e32 v15, v2
	v_mov_b32_e32 v16, v2
	v_mov_b32_e32 v17, v2
	v_mov_b32_e32 v26, v2
	v_mov_b32_e32 v27, v2
	v_mov_b32_e32 v28, v2
	v_mov_b32_e32 v29, v2
	v_mov_b32_e32 v30, v2
	v_mov_b32_e32 v31, v2
	v_mov_b32_e32 v32, v2
	v_mov_b32_e32 v33, v2
	v_mov_b32_e32 v42, v2
	v_mov_b32_e32 v43, v2
	v_mov_b32_e32 v44, v2
	v_mov_b32_e32 v45, v2
	v_mov_b32_e32 v46, v2
	v_mov_b32_e32 v47, v2
	v_mov_b32_e32 v48, v2
	v_mov_b32_e32 v49, v2
	v_mov_b32_e32 v58, v2
	v_mov_b32_e32 v59, v2
	v_mov_b32_e32 v60, v2
	v_mov_b32_e32 v61, v2
	v_mov_b32_e32 v62, v2
	v_mov_b32_e32 v63, v2
	v_mov_b32_e32 v64, v2
	v_mov_b32_e32 v65, v2
	v_mov_b32_e32 v66, v2
	v_mov_b32_e32 v67, v2
	v_mov_b32_e32 v68, v2
	v_mov_b32_e32 v69, v2
	v_mov_b32_e32 v70, v2
	v_mov_b32_e32 v71, v2
	v_mov_b32_e32 v72, v2
	v_mov_b32_e32 v73, v2
	v_mov_b32_e32 v82, v2
	v_mov_b32_e32 v83, v2
	v_mov_b32_e32 v84, v2
	v_mov_b32_e32 v85, v2
	v_mov_b32_e32 v86, v2
	v_mov_b32_e32 v87, v2
	v_mov_b32_e32 v88, v2
	v_mov_b32_e32 v89, v2
	v_mov_b32_e32 v98, v2
	v_mov_b32_e32 v99, v2
	v_mov_b32_e32 v100, v2
	v_mov_b32_e32 v101, v2
	v_mov_b32_e32 v102, v2
	v_mov_b32_e32 v103, v2
	v_mov_b32_e32 v104, v2
	v_mov_b32_e32 v105, v2
	v_mov_b32_e32 v114, v2
	v_mov_b32_e32 v115, v2
	v_mov_b32_e32 v116, v2
	v_mov_b32_e32 v117, v2
	v_mov_b32_e32 v118, v2
	v_mov_b32_e32 v119, v2
	v_mov_b32_e32 v120, v2
	v_mov_b32_e32 v121, v2
	v_mov_b32_e32 v74, v2
	v_mov_b32_e32 v75, v2
	v_mov_b32_e32 v76, v2
	v_mov_b32_e32 v77, v2
	v_mov_b32_e32 v78, v2
	v_mov_b32_e32 v79, v2
	v_mov_b32_e32 v80, v2
	v_mov_b32_e32 v81, v2
	v_mov_b32_e32 v90, v2
	v_mov_b32_e32 v91, v2
	v_mov_b32_e32 v92, v2
	v_mov_b32_e32 v93, v2
	v_mov_b32_e32 v94, v2
	v_mov_b32_e32 v95, v2
	v_mov_b32_e32 v96, v2
	v_mov_b32_e32 v97, v2
	v_mov_b32_e32 v106, v2
	v_mov_b32_e32 v107, v2
	v_mov_b32_e32 v108, v2
	v_mov_b32_e32 v109, v2
	v_mov_b32_e32 v110, v2
	v_mov_b32_e32 v111, v2
	v_mov_b32_e32 v112, v2
	v_mov_b32_e32 v113, v2
	v_mov_b32_e32 v122, v2
	v_mov_b32_e32 v123, v2
	v_mov_b32_e32 v124, v2
	v_mov_b32_e32 v125, v2
	v_mov_b32_e32 v134, v2
	v_mov_b32_e32 v135, v2
	v_mov_b32_e32 v136, v2
	v_mov_b32_e32 v137, v2
	s_branch .LBB0_455

.LBB0_619:
	ds_read_b128 v[38:41], v210
	ds_read_b128 v[42:45], v210 offset:1024
	ds_read_b128 v[46:49], v210 offset:2048
	ds_read_b128 v[58:61], v210 offset:3072
	ds_read_b128 v[142:145], v211
	ds_read_b128 v[146:149], v211 offset:1024
	ds_read_b128 v[150:153], v211 offset:2048
	ds_read_b128 v[154:157], v211 offset:3072
	s_add_i32 s6, s1, 0xfffe0080
	s_cmp_eq_u32 s3, 4
	s_cselect_b32 s8, s75, s6
	s_cselect_b32 s7, s0, s2
	s_add_i32 s6, s8, 0x80
	s_mov_b32 m0, s68
	s_nop 0
	buffer_load_dwordx4 v206, s[16:19], s1 offen lds
	s_nop 0
	s_mov_b32 m0, s69
	s_nop 0
	buffer_load_dwordx4 v207, s[16:19], s1 offen lds
	ds_read_b128 v[166:169], v212
	ds_read_b128 v[170:173], v212 offset:1024
	ds_read_b128 v[174:177], v212 offset:2048
	ds_read_b128 v[178:181], v212 offset:3072
	ds_read_b128 v[190:193], v212 offset:4096
	ds_read_b128 v[194:197], v212 offset:5120
	ds_read_b128 v[198:201], v212 offset:6144
	ds_read_b128 v[216:219], v212 offset:7168
	s_waitcnt vmcnt(8)
	s_waitcnt lgkmcnt(0)
	s_barrier
	s_setprio 1
	v_mfma_i32_16x16x64_i8 v[162:165], v[38:41], v[166:169], v[162:165]
	v_mfma_i32_16x16x64_i8 v[158:161], v[46:49], v[166:169], v[158:161]
	v_mfma_i32_16x16x64_i8 v[130:133], v[38:41], v[174:177], v[130:133]
	v_mfma_i32_16x16x64_i8 v[126:129], v[46:49], v[174:177], v[126:129]
	v_mfma_i32_16x16x64_i8 v[114:117], v[38:41], v[190:193], v[114:117]
	v_mfma_i32_16x16x64_i8 v[110:113], v[46:49], v[190:193], v[110:113]
	v_mfma_i32_16x16x64_i8 v[98:101], v[38:41], v[198:201], v[98:101]
	v_mfma_i32_16x16x64_i8 v[94:97], v[46:49], v[198:201], v[94:97]
	v_mfma_i32_16x16x64_i8 v[162:165], v[42:45], v[170:173], v[162:165]
	v_mfma_i32_16x16x64_i8 v[158:161], v[58:61], v[170:173], v[158:161]
	v_mfma_i32_16x16x64_i8 v[130:133], v[42:45], v[178:181], v[130:133]
	v_mfma_i32_16x16x64_i8 v[126:129], v[58:61], v[178:181], v[126:129]
	v_mfma_i32_16x16x64_i8 v[114:117], v[42:45], v[194:197], v[114:117]
	v_mfma_i32_16x16x64_i8 v[110:113], v[58:61], v[194:197], v[110:113]
	v_mfma_i32_16x16x64_i8 v[98:101], v[42:45], v[216:219], v[98:101]
	v_mfma_i32_16x16x64_i8 v[94:97], v[58:61], v[216:219], v[94:97]
	s_setprio 0
	s_setprio 1
	v_mfma_i32_16x16x64_i8 v[138:141], v[142:145], v[166:169], v[138:141]
	v_mfma_i32_16x16x64_i8 v[134:137], v[150:153], v[166:169], v[134:137]
	v_mfma_i32_16x16x64_i8 v[122:125], v[142:145], v[174:177], v[122:125]
	v_mfma_i32_16x16x64_i8 v[118:121], v[150:153], v[174:177], v[118:121]
	v_mfma_i32_16x16x64_i8 v[106:109], v[142:145], v[190:193], v[106:109]
	v_mfma_i32_16x16x64_i8 v[102:105], v[150:153], v[190:193], v[102:105]
	v_mfma_i32_16x16x64_i8 v[90:93], v[142:145], v[198:201], v[90:93]
	v_mfma_i32_16x16x64_i8 v[86:89], v[150:153], v[198:201], v[86:89]
	v_mfma_i32_16x16x64_i8 v[138:141], v[146:149], v[170:173], v[138:141]
	v_mfma_i32_16x16x64_i8 v[134:137], v[154:157], v[170:173], v[134:137]
	v_mfma_i32_16x16x64_i8 v[122:125], v[146:149], v[178:181], v[122:125]
	v_mfma_i32_16x16x64_i8 v[118:121], v[154:157], v[178:181], v[118:121]
	v_mfma_i32_16x16x64_i8 v[106:109], v[146:149], v[194:197], v[106:109]
	v_mfma_i32_16x16x64_i8 v[102:105], v[154:157], v[194:197], v[102:105]
	v_mfma_i32_16x16x64_i8 v[90:93], v[146:149], v[216:219], v[90:93]
	v_mfma_i32_16x16x64_i8 v[86:89], v[154:157], v[216:219], v[86:89]
	s_barrier
	s_setprio 0
	ds_read_b128 v[166:169], v212 offset:16384
	ds_read_b128 v[170:173], v212 offset:17408
	s_mov_b32 m0, s48
	s_nop 0
	buffer_load_dwordx4 v204, s[12:15], s7 offen lds
	ds_read_b128 v[174:177], v212 offset:18432
	ds_read_b128 v[178:181], v212 offset:19456
	s_add_i32 s9, s7, 0x20000
	s_mov_b32 m0, s49
	s_nop 0
	buffer_load_dwordx4 v205, s[12:15], s7 offen lds
	ds_read_b128 v[190:193], v212 offset:20480
	ds_read_b128 v[194:197], v212 offset:21504
	s_nop 0
	s_mov_b32 m0, s50
	s_nop 0
	buffer_load_dwordx4 v204, s[12:15], s9 offen lds
	ds_read_b128 v[198:201], v212 offset:22528
	ds_read_b128 v[216:219], v212 offset:23552
	s_nop 0
	s_mov_b32 m0, s51
	s_nop 0
	buffer_load_dwordx4 v205, s[12:15], s9 offen lds
	s_nop 0
	s_mov_b32 m0, s47
	s_nop 0
	buffer_load_dwordx4 v206, s[16:19], s8 offen lds
	s_nop 0
	s_mov_b32 m0, s52
	s_nop 0
	buffer_load_dwordx4 v207, s[16:19], s8 offen lds
	s_waitcnt vmcnt(8)
	s_waitcnt lgkmcnt(0)
	s_barrier
	s_setprio 1
	v_mfma_i32_16x16x64_i8 v[82:85], v[38:41], v[166:169], v[82:85]
	v_mfma_i32_16x16x64_i8 v[78:81], v[46:49], v[166:169], v[78:81]
	v_mfma_i32_16x16x64_i8 v[66:69], v[38:41], v[174:177], v[66:69]
	v_mfma_i32_16x16x64_i8 v[62:65], v[46:49], v[174:177], v[62:65]
	v_mfma_i32_16x16x64_i8 v[34:37], v[38:41], v[190:193], v[34:37]
	v_mfma_i32_16x16x64_i8 v[30:33], v[46:49], v[190:193], v[30:33]
	v_mfma_i32_16x16x64_i8 v[18:21], v[38:41], v[198:201], v[18:21]
	v_mfma_i32_16x16x64_i8 v[14:17], v[46:49], v[198:201], v[14:17]
	v_mfma_i32_16x16x64_i8 v[82:85], v[42:45], v[170:173], v[82:85]
	v_mfma_i32_16x16x64_i8 v[78:81], v[58:61], v[170:173], v[78:81]
	v_mfma_i32_16x16x64_i8 v[66:69], v[42:45], v[178:181], v[66:69]
	v_mfma_i32_16x16x64_i8 v[62:65], v[58:61], v[178:181], v[62:65]
	v_mfma_i32_16x16x64_i8 v[34:37], v[42:45], v[194:197], v[34:37]
	v_mfma_i32_16x16x64_i8 v[30:33], v[58:61], v[194:197], v[30:33]
	v_mfma_i32_16x16x64_i8 v[18:21], v[42:45], v[216:219], v[18:21]
	v_mfma_i32_16x16x64_i8 v[14:17], v[58:61], v[216:219], v[14:17]
	s_setprio 0
	s_setprio 1
	v_mfma_i32_16x16x64_i8 v[50:53], v[150:153], v[174:177], v[50:53]
	v_mfma_i32_16x16x64_i8 v[26:29], v[142:145], v[190:193], v[26:29]
	v_mfma_i32_16x16x64_i8 v[22:25], v[150:153], v[190:193], v[22:25]
	v_mfma_i32_16x16x64_i8 v[10:13], v[142:145], v[198:201], v[10:13]
	v_mfma_i32_16x16x64_i8 v[4:7], v[150:153], v[198:201], v[6:9]
	v_mfma_i32_16x16x64_i8 v[38:41], v[142:145], v[166:169], v[74:77]
	v_mfma_i32_16x16x64_i8 v[42:45], v[150:153], v[166:169], v[70:73]
	v_mfma_i32_16x16x64_i8 v[46:49], v[142:145], v[174:177], v[54:57]
	v_mfma_i32_16x16x64_i8 v[50:53], v[154:157], v[178:181], v[50:53]
	v_mfma_i32_16x16x64_i8 v[26:29], v[146:149], v[194:197], v[26:29]
	v_mfma_i32_16x16x64_i8 v[22:25], v[154:157], v[194:197], v[22:25]
	v_mfma_i32_16x16x64_i8 v[10:13], v[146:149], v[216:219], v[10:13]
	v_mfma_i32_16x16x64_i8 v[4:7], v[154:157], v[216:219], v[4:7]
	v_mfma_i32_16x16x64_i8 v[38:41], v[146:149], v[170:173], v[38:41]
	v_mfma_i32_16x16x64_i8 v[42:45], v[154:157], v[170:173], v[42:45]
	v_mfma_i32_16x16x64_i8 v[46:49], v[146:149], v[178:181], v[46:49]
	s_barrier
	s_setprio 0
	ds_read_b128 v[54:57], v213
	ds_read_b128 v[58:61], v213 offset:1024
	ds_read_b128 v[70:73], v213 offset:2048
	ds_read_b128 v[74:77], v213 offset:3072
	ds_read_b128 v[142:145], v214
	ds_read_b128 v[146:149], v214 offset:1024
	ds_read_b128 v[150:153], v214 offset:2048
	ds_read_b128 v[154:157], v214 offset:3072
	s_add_i32 s8, s8, 0x20000
	s_mov_b32 m0, s53
	s_nop 0
	buffer_load_dwordx4 v206, s[16:19], s8 offen lds
	s_nop 0
	s_mov_b32 m0, s54
	s_nop 0
	buffer_load_dwordx4 v207, s[16:19], s8 offen lds
	ds_read_b128 v[166:169], v212 offset:32768
	ds_read_b128 v[170:173], v212 offset:33792
	ds_read_b128 v[174:177], v212 offset:34816
	ds_read_b128 v[178:181], v212 offset:35840
	ds_read_b128 v[190:193], v212 offset:36864
	ds_read_b128 v[194:197], v212 offset:37888
	ds_read_b128 v[198:201], v212 offset:38912
	ds_read_b128 v[216:219], v212 offset:39936
	s_waitcnt vmcnt(8)
	s_waitcnt lgkmcnt(0)
	s_barrier
	s_setprio 1
	v_mfma_i32_16x16x64_i8 v[162:165], v[54:57], v[166:169], v[162:165]
	v_mfma_i32_16x16x64_i8 v[158:161], v[70:73], v[166:169], v[158:161]
	v_mfma_i32_16x16x64_i8 v[130:133], v[54:57], v[174:177], v[130:133]
	v_mfma_i32_16x16x64_i8 v[126:129], v[70:73], v[174:177], v[126:129]
	v_mfma_i32_16x16x64_i8 v[114:117], v[54:57], v[190:193], v[114:117]
	v_mfma_i32_16x16x64_i8 v[110:113], v[70:73], v[190:193], v[110:113]
	v_mfma_i32_16x16x64_i8 v[98:101], v[54:57], v[198:201], v[98:101]
	v_mfma_i32_16x16x64_i8 v[94:97], v[70:73], v[198:201], v[94:97]
	v_mfma_i32_16x16x64_i8 v[162:165], v[58:61], v[170:173], v[162:165]
	v_mfma_i32_16x16x64_i8 v[158:161], v[74:77], v[170:173], v[158:161]
	v_mfma_i32_16x16x64_i8 v[130:133], v[58:61], v[178:181], v[130:133]
	v_mfma_i32_16x16x64_i8 v[126:129], v[74:77], v[178:181], v[126:129]
	v_mfma_i32_16x16x64_i8 v[114:117], v[58:61], v[194:197], v[114:117]
	v_mfma_i32_16x16x64_i8 v[110:113], v[74:77], v[194:197], v[110:113]
	v_mfma_i32_16x16x64_i8 v[98:101], v[58:61], v[216:219], v[98:101]
	v_mfma_i32_16x16x64_i8 v[94:97], v[74:77], v[216:219], v[94:97]
	s_setprio 0
	s_setprio 1
	v_mfma_i32_16x16x64_i8 v[138:141], v[142:145], v[166:169], v[138:141]
	v_mfma_i32_16x16x64_i8 v[134:137], v[150:153], v[166:169], v[134:137]
	v_mfma_i32_16x16x64_i8 v[122:125], v[142:145], v[174:177], v[122:125]
	v_mfma_i32_16x16x64_i8 v[118:121], v[150:153], v[174:177], v[118:121]
	v_mfma_i32_16x16x64_i8 v[106:109], v[142:145], v[190:193], v[106:109]
	v_mfma_i32_16x16x64_i8 v[102:105], v[150:153], v[190:193], v[102:105]
	v_mfma_i32_16x16x64_i8 v[90:93], v[142:145], v[198:201], v[90:93]
	v_mfma_i32_16x16x64_i8 v[86:89], v[150:153], v[198:201], v[86:89]
	v_mfma_i32_16x16x64_i8 v[138:141], v[146:149], v[170:173], v[138:141]
	v_mfma_i32_16x16x64_i8 v[134:137], v[154:157], v[170:173], v[134:137]
	v_mfma_i32_16x16x64_i8 v[122:125], v[146:149], v[178:181], v[122:125]
	v_mfma_i32_16x16x64_i8 v[118:121], v[154:157], v[178:181], v[118:121]
	v_mfma_i32_16x16x64_i8 v[106:109], v[146:149], v[194:197], v[106:109]
	v_mfma_i32_16x16x64_i8 v[102:105], v[154:157], v[194:197], v[102:105]
	v_mfma_i32_16x16x64_i8 v[90:93], v[146:149], v[216:219], v[90:93]
	v_mfma_i32_16x16x64_i8 v[86:89], v[154:157], v[216:219], v[86:89]
	s_barrier
	s_setprio 0
	ds_read_b128 v[166:169], v212 offset:49152
	ds_read_b128 v[170:173], v212 offset:50176
	s_or_b32 s8, s7, 0x80
	s_mov_b32 m0, s62
	s_nop 0
	buffer_load_dwordx4 v204, s[12:15], s8 offen lds
	ds_read_b128 v[174:177], v212 offset:51200
	ds_read_b128 v[178:181], v212 offset:52224
	s_add_i32 s7, s7, 0x20080
	s_mov_b32 m0, s63
	s_nop 0
	buffer_load_dwordx4 v205, s[12:15], s8 offen lds
	ds_read_b128 v[190:193], v212 offset:53248
	ds_read_b128 v[194:197], v212 offset:54272
	s_nop 0
	s_mov_b32 m0, s66
	s_nop 0
	buffer_load_dwordx4 v204, s[12:15], s7 offen lds
	ds_read_b128 v[198:201], v212 offset:55296
	ds_read_b128 v[216:219], v212 offset:56320
	s_nop 0
	s_mov_b32 m0, s67
	s_nop 0
	buffer_load_dwordx4 v205, s[12:15], s7 offen lds
	s_nop 0
	s_mov_b32 m0, s64
	s_nop 0
	buffer_load_dwordx4 v206, s[16:19], s6 offen lds
	s_nop 0
	s_mov_b32 m0, s65
	s_nop 0
	buffer_load_dwordx4 v207, s[16:19], s6 offen lds
	s_waitcnt vmcnt(8)
	s_waitcnt lgkmcnt(0)
	s_barrier
	s_setprio 1
	v_mfma_i32_16x16x64_i8 v[82:85], v[54:57], v[166:169], v[82:85]
	v_mfma_i32_16x16x64_i8 v[78:81], v[70:73], v[166:169], v[78:81]
	v_mfma_i32_16x16x64_i8 v[66:69], v[54:57], v[174:177], v[66:69]
	v_mfma_i32_16x16x64_i8 v[62:65], v[70:73], v[174:177], v[62:65]
	v_mfma_i32_16x16x64_i8 v[34:37], v[54:57], v[190:193], v[34:37]
	v_mfma_i32_16x16x64_i8 v[30:33], v[70:73], v[190:193], v[30:33]
	v_mfma_i32_16x16x64_i8 v[18:21], v[54:57], v[198:201], v[18:21]
	v_mfma_i32_16x16x64_i8 v[14:17], v[70:73], v[198:201], v[14:17]
	v_mfma_i32_16x16x64_i8 v[82:85], v[58:61], v[170:173], v[82:85]
	v_mfma_i32_16x16x64_i8 v[78:81], v[74:77], v[170:173], v[78:81]
	v_mfma_i32_16x16x64_i8 v[66:69], v[58:61], v[178:181], v[66:69]
	v_mfma_i32_16x16x64_i8 v[62:65], v[74:77], v[178:181], v[62:65]
	v_mfma_i32_16x16x64_i8 v[34:37], v[58:61], v[194:197], v[34:37]
	v_mfma_i32_16x16x64_i8 v[30:33], v[74:77], v[194:197], v[30:33]
	v_mfma_i32_16x16x64_i8 v[18:21], v[58:61], v[216:219], v[18:21]
	v_mfma_i32_16x16x64_i8 v[14:17], v[74:77], v[216:219], v[14:17]
	s_setprio 0
	s_setprio 1
	v_mfma_i32_16x16x64_i8 v[38:41], v[142:145], v[166:169], v[38:41]
	v_mfma_i32_16x16x64_i8 v[74:77], v[146:149], v[170:173], v[38:41]
	v_mfma_i32_16x16x64_i8 v[38:41], v[150:153], v[166:169], v[42:45]
	v_mfma_i32_16x16x64_i8 v[70:73], v[154:157], v[170:173], v[38:41]
	v_mfma_i32_16x16x64_i8 v[38:41], v[142:145], v[174:177], v[46:49]
	v_mfma_i32_16x16x64_i8 v[54:57], v[146:149], v[178:181], v[38:41]
	v_mfma_i32_16x16x64_i8 v[38:41], v[150:153], v[174:177], v[50:53]
	v_mfma_i32_16x16x64_i8 v[26:29], v[142:145], v[190:193], v[26:29]
	v_mfma_i32_16x16x64_i8 v[22:25], v[150:153], v[190:193], v[22:25]
	v_mfma_i32_16x16x64_i8 v[8:11], v[142:145], v[198:201], v[10:13]
	v_mfma_i32_16x16x64_i8 v[4:7], v[150:153], v[198:201], v[4:7]
	v_mfma_i32_16x16x64_i8 v[50:53], v[154:157], v[178:181], v[38:41]
	v_mfma_i32_16x16x64_i8 v[26:29], v[146:149], v[194:197], v[26:29]
	v_mfma_i32_16x16x64_i8 v[22:25], v[154:157], v[194:197], v[22:25]
	v_mfma_i32_16x16x64_i8 v[10:13], v[146:149], v[216:219], v[8:11]
	v_mfma_i32_16x16x64_i8 v[6:9], v[154:157], v[216:219], v[4:7]
	s_barrier
	s_setprio 0
	s_add_i32 s3, s3, 2
	s_addk_i32 s1, 0x100
	s_addk_i32 s2, 0x100
	s_cmp_gt_u32 s3, 5
	s_cbranch_scc0 .LBB0_619
	s_and_b64 vcc, exec, s[34:35]
	s_cbranch_vccz .LBB0_622
	s_barrier

.LBB0_943:
	v_add_u32_e32 v150, 0x10000, v8
	v_add_u32_e32 v166, 0x14000, v8
	ds_read_b128 v[10:13], v150
	ds_read_b128 v[14:17], v150 offset:1024
	ds_read_b128 v[146:149], v150 offset:2048
	ds_read_b128 v[150:153], v150 offset:3072
	ds_read_b128 v[154:157], v166
	ds_read_b128 v[158:161], v166 offset:1024
	ds_read_b128 v[162:165], v166 offset:2048
	ds_read_b128 v[166:169], v166 offset:3072
	s_add_i32 s61, s37, s58
	s_add_i32 s60, s33, s58
	s_add_i32 s59, s61, 0x400
	s_addk_i32 s60, 0x400
	s_cmp_eq_u32 s58, 0
	s_cselect_b32 s62, s53, s59
	s_cselect_b32 s60, s54, s60
	s_or_b32 s59, s62, 0x80
	s_add_i32 s61, s61, 0x20380
	s_mov_b32 m0, s48
	s_nop 0
	buffer_load_dwordx4 v6, s[12:15], s61 offen lds
	s_nop 0
	s_mov_b32 m0, s49
	s_nop 0
	buffer_load_dwordx4 v7, s[12:15], s61 offen lds
	ds_read_b128 v[170:173], v9
	ds_read_b128 v[174:177], v9 offset:1024
	ds_read_b128 v[178:181], v9 offset:2048
	ds_read_b128 v[182:185], v9 offset:3072
	ds_read_b128 v[186:189], v9 offset:4096
	ds_read_b128 v[190:193], v9 offset:5120
	ds_read_b128 v[194:197], v9 offset:6144
	ds_read_b128 v[198:201], v9 offset:7168
	s_waitcnt vmcnt(8)
	s_waitcnt lgkmcnt(0)
	s_barrier
	s_setprio 1
	v_mfma_i32_16x16x64_i8 v[142:145], v[10:13], v[170:173], v[142:145]
	v_mfma_i32_16x16x64_i8 v[138:141], v[146:149], v[170:173], v[138:141]
	v_mfma_i32_16x16x64_i8 v[126:129], v[10:13], v[178:181], v[126:129]
	v_mfma_i32_16x16x64_i8 v[122:125], v[146:149], v[178:181], v[122:125]
	v_mfma_i32_16x16x64_i8 v[110:113], v[10:13], v[186:189], v[110:113]
	v_mfma_i32_16x16x64_i8 v[106:109], v[146:149], v[186:189], v[106:109]
	v_mfma_i32_16x16x64_i8 v[94:97], v[10:13], v[194:197], v[94:97]
	v_mfma_i32_16x16x64_i8 v[90:93], v[146:149], v[194:197], v[90:93]
	v_mfma_i32_16x16x64_i8 v[142:145], v[14:17], v[174:177], v[142:145]
	v_mfma_i32_16x16x64_i8 v[138:141], v[150:153], v[174:177], v[138:141]
	v_mfma_i32_16x16x64_i8 v[126:129], v[14:17], v[182:185], v[126:129]
	v_mfma_i32_16x16x64_i8 v[122:125], v[150:153], v[182:185], v[122:125]
	v_mfma_i32_16x16x64_i8 v[110:113], v[14:17], v[190:193], v[110:113]
	v_mfma_i32_16x16x64_i8 v[106:109], v[150:153], v[190:193], v[106:109]
	v_mfma_i32_16x16x64_i8 v[94:97], v[14:17], v[198:201], v[94:97]
	v_mfma_i32_16x16x64_i8 v[90:93], v[150:153], v[198:201], v[90:93]
	s_setprio 0
	s_setprio 1
	v_mfma_i32_16x16x64_i8 v[134:137], v[154:157], v[170:173], v[134:137]
	v_mfma_i32_16x16x64_i8 v[130:133], v[162:165], v[170:173], v[130:133]
	v_mfma_i32_16x16x64_i8 v[118:121], v[154:157], v[178:181], v[118:121]
	v_mfma_i32_16x16x64_i8 v[114:117], v[162:165], v[178:181], v[114:117]
	v_mfma_i32_16x16x64_i8 v[102:105], v[154:157], v[186:189], v[102:105]
	v_mfma_i32_16x16x64_i8 v[98:101], v[162:165], v[186:189], v[98:101]
	v_mfma_i32_16x16x64_i8 v[86:89], v[154:157], v[194:197], v[86:89]
	v_mfma_i32_16x16x64_i8 v[82:85], v[162:165], v[194:197], v[82:85]
	v_mfma_i32_16x16x64_i8 v[134:137], v[158:161], v[174:177], v[134:137]
	v_mfma_i32_16x16x64_i8 v[130:133], v[166:169], v[174:177], v[130:133]
	v_mfma_i32_16x16x64_i8 v[118:121], v[158:161], v[182:185], v[118:121]
	v_mfma_i32_16x16x64_i8 v[114:117], v[166:169], v[182:185], v[114:117]
	v_mfma_i32_16x16x64_i8 v[102:105], v[158:161], v[190:193], v[102:105]
	v_mfma_i32_16x16x64_i8 v[98:101], v[166:169], v[190:193], v[98:101]
	v_mfma_i32_16x16x64_i8 v[86:89], v[158:161], v[198:201], v[86:89]
	v_mfma_i32_16x16x64_i8 v[82:85], v[166:169], v[198:201], v[82:85]
	s_barrier
	s_setprio 0
	ds_read_b128 v[170:173], v9 offset:16384
	ds_read_b128 v[174:177], v9 offset:17408
	s_mov_b32 m0, s29
	s_nop 0
	buffer_load_dwordx4 v6, s[8:11], s60 offen lds
	ds_read_b128 v[178:181], v9 offset:18432
	ds_read_b128 v[182:185], v9 offset:19456
	s_add_i32 s61, s60, 0x20000
	s_mov_b32 m0, s34
	s_nop 0
	buffer_load_dwordx4 v7, s[8:11], s60 offen lds
	ds_read_b128 v[186:189], v9 offset:20480
	ds_read_b128 v[190:193], v9 offset:21504
	s_nop 0
	s_mov_b32 m0, s35
	s_nop 0
	buffer_load_dwordx4 v6, s[8:11], s61 offen lds
	ds_read_b128 v[194:197], v9 offset:22528
	ds_read_b128 v[198:201], v9 offset:23552
	s_nop 0
	s_mov_b32 m0, s36
	s_nop 0
	buffer_load_dwordx4 v7, s[8:11], s61 offen lds
	s_nop 0
	s_mov_b32 m0, s28
	s_nop 0
	buffer_load_dwordx4 v6, s[12:15], s62 offen lds
	s_nop 0
	s_mov_b32 m0, s38
	s_nop 0
	buffer_load_dwordx4 v7, s[12:15], s62 offen lds
	s_waitcnt vmcnt(8)
	s_waitcnt lgkmcnt(0)
	s_barrier
	s_setprio 1
	v_mfma_i32_16x16x64_i8 v[78:81], v[10:13], v[170:173], v[78:81]
	v_mfma_i32_16x16x64_i8 v[74:77], v[146:149], v[170:173], v[74:77]
	v_mfma_i32_16x16x64_i8 v[62:65], v[10:13], v[178:181], v[62:65]
	v_mfma_i32_16x16x64_i8 v[58:61], v[146:149], v[178:181], v[58:61]
	v_mfma_i32_16x16x64_i8 v[46:49], v[10:13], v[186:189], v[46:49]
	v_mfma_i32_16x16x64_i8 v[42:45], v[146:149], v[186:189], v[42:45]
	v_mfma_i32_16x16x64_i8 v[10:13], v[10:13], v[194:197], v[30:33]
	v_mfma_i32_16x16x64_i8 v[78:81], v[14:17], v[174:177], v[78:81]
	v_mfma_i32_16x16x64_i8 v[74:77], v[150:153], v[174:177], v[74:77]
	v_mfma_i32_16x16x64_i8 v[62:65], v[14:17], v[182:185], v[62:65]
	v_mfma_i32_16x16x64_i8 v[58:61], v[150:153], v[182:185], v[58:61]
	v_mfma_i32_16x16x64_i8 v[46:49], v[14:17], v[190:193], v[46:49]
	v_mfma_i32_16x16x64_i8 v[42:45], v[150:153], v[190:193], v[42:45]
	v_mfma_i32_16x16x64_i8 v[10:13], v[14:17], v[198:201], v[10:13]
	v_mfma_i32_16x16x64_i8 v[14:17], v[146:149], v[194:197], v[26:29]
	v_mfma_i32_16x16x64_i8 v[14:17], v[150:153], v[198:201], v[14:17]
	s_setprio 0
	s_setprio 1
	v_mfma_i32_16x16x64_i8 v[26:29], v[154:157], v[170:173], v[70:73]
	v_mfma_i32_16x16x64_i8 v[70:73], v[158:161], v[174:177], v[26:29]
	v_mfma_i32_16x16x64_i8 v[26:29], v[162:165], v[170:173], v[66:69]
	v_mfma_i32_16x16x64_i8 v[66:69], v[166:169], v[174:177], v[26:29]
	v_mfma_i32_16x16x64_i8 v[26:29], v[154:157], v[178:181], v[54:57]
	v_mfma_i32_16x16x64_i8 v[54:57], v[158:161], v[182:185], v[26:29]
	v_mfma_i32_16x16x64_i8 v[26:29], v[162:165], v[178:181], v[50:53]
	v_mfma_i32_16x16x64_i8 v[50:53], v[166:169], v[182:185], v[26:29]
	v_mfma_i32_16x16x64_i8 v[26:29], v[154:157], v[186:189], v[38:41]
	v_mfma_i32_16x16x64_i8 v[38:41], v[158:161], v[190:193], v[26:29]
	v_mfma_i32_16x16x64_i8 v[26:29], v[162:165], v[186:189], v[34:37]
	v_mfma_i32_16x16x64_i8 v[22:25], v[154:157], v[194:197], v[22:25]
	v_mfma_i32_16x16x64_i8 v[18:21], v[162:165], v[194:197], v[18:21]
	v_mfma_i32_16x16x64_i8 v[34:37], v[166:169], v[190:193], v[26:29]
	v_mfma_i32_16x16x64_i8 v[22:25], v[158:161], v[198:201], v[22:25]
	v_mfma_i32_16x16x64_i8 v[18:21], v[166:169], v[198:201], v[18:21]
	s_barrier
	s_setprio 0
	v_add_u32_e32 v150, 0x18000, v8
	v_add_u32_e32 v166, 0x1c000, v8
	ds_read_b128 v[26:29], v150
	ds_read_b128 v[30:33], v150 offset:1024
	ds_read_b128 v[146:149], v150 offset:2048
	ds_read_b128 v[150:153], v150 offset:3072
	ds_read_b128 v[154:157], v166
	ds_read_b128 v[158:161], v166 offset:1024
	ds_read_b128 v[162:165], v166 offset:2048
	ds_read_b128 v[166:169], v166 offset:3072
	s_add_i32 s61, s62, 0x20000
	s_mov_b32 m0, s40
	s_nop 0
	buffer_load_dwordx4 v6, s[12:15], s61 offen lds
	s_nop 0
	s_mov_b32 m0, s41
	s_nop 0
	buffer_load_dwordx4 v7, s[12:15], s61 offen lds
	ds_read_b128 v[170:173], v9 offset:32768
	ds_read_b128 v[174:177], v9 offset:33792
	ds_read_b128 v[178:181], v9 offset:34816
	ds_read_b128 v[182:185], v9 offset:35840
	ds_read_b128 v[186:189], v9 offset:36864
	ds_read_b128 v[190:193], v9 offset:37888
	ds_read_b128 v[194:197], v9 offset:38912
	ds_read_b128 v[198:201], v9 offset:39936
	s_waitcnt vmcnt(8)
	s_waitcnt lgkmcnt(0)
	s_barrier
	s_setprio 1
	v_mfma_i32_16x16x64_i8 v[142:145], v[26:29], v[170:173], v[142:145]
	v_mfma_i32_16x16x64_i8 v[138:141], v[146:149], v[170:173], v[138:141]
	v_mfma_i32_16x16x64_i8 v[126:129], v[26:29], v[178:181], v[126:129]
	v_mfma_i32_16x16x64_i8 v[122:125], v[146:149], v[178:181], v[122:125]
	v_mfma_i32_16x16x64_i8 v[110:113], v[26:29], v[186:189], v[110:113]
	v_mfma_i32_16x16x64_i8 v[106:109], v[146:149], v[186:189], v[106:109]
	v_mfma_i32_16x16x64_i8 v[94:97], v[26:29], v[194:197], v[94:97]
	v_mfma_i32_16x16x64_i8 v[90:93], v[146:149], v[194:197], v[90:93]
	v_mfma_i32_16x16x64_i8 v[142:145], v[30:33], v[174:177], v[142:145]
	v_mfma_i32_16x16x64_i8 v[138:141], v[150:153], v[174:177], v[138:141]
	v_mfma_i32_16x16x64_i8 v[126:129], v[30:33], v[182:185], v[126:129]
	v_mfma_i32_16x16x64_i8 v[122:125], v[150:153], v[182:185], v[122:125]
	v_mfma_i32_16x16x64_i8 v[110:113], v[30:33], v[190:193], v[110:113]
	v_mfma_i32_16x16x64_i8 v[106:109], v[150:153], v[190:193], v[106:109]
	v_mfma_i32_16x16x64_i8 v[94:97], v[30:33], v[198:201], v[94:97]
	v_mfma_i32_16x16x64_i8 v[90:93], v[150:153], v[198:201], v[90:93]
	s_setprio 0
	s_setprio 1
	v_mfma_i32_16x16x64_i8 v[134:137], v[154:157], v[170:173], v[134:137]
	v_mfma_i32_16x16x64_i8 v[130:133], v[162:165], v[170:173], v[130:133]
	v_mfma_i32_16x16x64_i8 v[118:121], v[154:157], v[178:181], v[118:121]
	v_mfma_i32_16x16x64_i8 v[114:117], v[162:165], v[178:181], v[114:117]
	v_mfma_i32_16x16x64_i8 v[102:105], v[154:157], v[186:189], v[102:105]
	v_mfma_i32_16x16x64_i8 v[98:101], v[162:165], v[186:189], v[98:101]
	v_mfma_i32_16x16x64_i8 v[86:89], v[154:157], v[194:197], v[86:89]
	v_mfma_i32_16x16x64_i8 v[82:85], v[162:165], v[194:197], v[82:85]
	v_mfma_i32_16x16x64_i8 v[134:137], v[158:161], v[174:177], v[134:137]
	v_mfma_i32_16x16x64_i8 v[130:133], v[166:169], v[174:177], v[130:133]
	v_mfma_i32_16x16x64_i8 v[118:121], v[158:161], v[182:185], v[118:121]
	v_mfma_i32_16x16x64_i8 v[114:117], v[166:169], v[182:185], v[114:117]
	v_mfma_i32_16x16x64_i8 v[102:105], v[158:161], v[190:193], v[102:105]
	v_mfma_i32_16x16x64_i8 v[98:101], v[166:169], v[190:193], v[98:101]
	v_mfma_i32_16x16x64_i8 v[86:89], v[158:161], v[198:201], v[86:89]
	v_mfma_i32_16x16x64_i8 v[82:85], v[166:169], v[198:201], v[82:85]
	s_barrier
	s_setprio 0
	ds_read_b128 v[170:173], v9 offset:49152
	ds_read_b128 v[174:177], v9 offset:50176
	s_or_b32 s61, s60, 0x80
	s_mov_b32 m0, s42
	s_nop 0
	buffer_load_dwordx4 v6, s[8:11], s61 offen lds
	ds_read_b128 v[178:181], v9 offset:51200
	ds_read_b128 v[182:185], v9 offset:52224
	s_add_i32 s60, s60, 0x20080
	s_mov_b32 m0, s43
	s_nop 0
	buffer_load_dwordx4 v7, s[8:11], s61 offen lds
	ds_read_b128 v[186:189], v9 offset:53248
	ds_read_b128 v[190:193], v9 offset:54272
	s_nop 0
	s_mov_b32 m0, s46
	s_nop 0
	buffer_load_dwordx4 v6, s[8:11], s60 offen lds
	ds_read_b128 v[194:197], v9 offset:55296
	ds_read_b128 v[198:201], v9 offset:56320
	s_nop 0
	s_mov_b32 m0, s47
	s_nop 0
	buffer_load_dwordx4 v7, s[8:11], s60 offen lds
	s_nop 0
	s_mov_b32 m0, s44
	s_nop 0
	buffer_load_dwordx4 v6, s[12:15], s59 offen lds
	s_nop 0
	s_mov_b32 m0, s45
	s_nop 0
	buffer_load_dwordx4 v7, s[12:15], s59 offen lds
	s_waitcnt vmcnt(8)
	s_waitcnt lgkmcnt(0)
	s_barrier
	s_setprio 1
	v_mfma_i32_16x16x64_i8 v[78:81], v[26:29], v[170:173], v[78:81]
	v_mfma_i32_16x16x64_i8 v[62:65], v[26:29], v[178:181], v[62:65]
	v_mfma_i32_16x16x64_i8 v[46:49], v[26:29], v[186:189], v[46:49]
	v_mfma_i32_16x16x64_i8 v[10:13], v[26:29], v[194:197], v[10:13]
	v_mfma_i32_16x16x64_i8 v[78:81], v[30:33], v[174:177], v[78:81]
	v_mfma_i32_16x16x64_i8 v[74:77], v[146:149], v[170:173], v[74:77]
	v_mfma_i32_16x16x64_i8 v[62:65], v[30:33], v[182:185], v[62:65]
	v_mfma_i32_16x16x64_i8 v[58:61], v[146:149], v[178:181], v[58:61]
	v_mfma_i32_16x16x64_i8 v[46:49], v[30:33], v[190:193], v[46:49]
	v_mfma_i32_16x16x64_i8 v[42:45], v[146:149], v[186:189], v[42:45]
	v_mfma_i32_16x16x64_i8 v[30:33], v[30:33], v[198:201], v[10:13]
	v_mfma_i32_16x16x64_i8 v[10:13], v[146:149], v[194:197], v[14:17]
	v_mfma_i32_16x16x64_i8 v[74:77], v[150:153], v[174:177], v[74:77]
	v_mfma_i32_16x16x64_i8 v[58:61], v[150:153], v[182:185], v[58:61]
	v_mfma_i32_16x16x64_i8 v[42:45], v[150:153], v[190:193], v[42:45]
	v_mfma_i32_16x16x64_i8 v[26:29], v[150:153], v[198:201], v[10:13]
	s_setprio 0
	s_setprio 1
	v_mfma_i32_16x16x64_i8 v[10:13], v[154:157], v[170:173], v[70:73]
	v_mfma_i32_16x16x64_i8 v[70:73], v[158:161], v[174:177], v[10:13]
	v_mfma_i32_16x16x64_i8 v[10:13], v[162:165], v[170:173], v[66:69]
	v_mfma_i32_16x16x64_i8 v[66:69], v[166:169], v[174:177], v[10:13]
	v_mfma_i32_16x16x64_i8 v[10:13], v[154:157], v[178:181], v[54:57]
	v_mfma_i32_16x16x64_i8 v[54:57], v[158:161], v[182:185], v[10:13]
	v_mfma_i32_16x16x64_i8 v[10:13], v[162:165], v[178:181], v[50:53]
	v_mfma_i32_16x16x64_i8 v[50:53], v[166:169], v[182:185], v[10:13]
	v_mfma_i32_16x16x64_i8 v[10:13], v[154:157], v[186:189], v[38:41]
	v_mfma_i32_16x16x64_i8 v[38:41], v[158:161], v[190:193], v[10:13]
	v_mfma_i32_16x16x64_i8 v[10:13], v[162:165], v[186:189], v[34:37]
	v_mfma_i32_16x16x64_i8 v[34:37], v[166:169], v[190:193], v[10:13]
	v_mfma_i32_16x16x64_i8 v[10:13], v[154:157], v[194:197], v[22:25]
	v_mfma_i32_16x16x64_i8 v[22:25], v[158:161], v[198:201], v[10:13]
	v_mfma_i32_16x16x64_i8 v[10:13], v[162:165], v[194:197], v[18:21]
	v_mfma_i32_16x16x64_i8 v[18:21], v[166:169], v[198:201], v[10:13]
	s_barrier
	s_setprio 0
	s_add_i32 s55, s55, 2
	s_addk_i32 s58, 0x100
	s_cmp_lt_u32 s55, 6
	s_cbranch_scc1 .LBB0_943
	s_andn2_b64 vcc, exec, s[6:7]
	s_cbranch_vccz .LBB0_935
	v_cvt_f32_i32_e32 v142, v142
	v_cvt_f32_i32_e32 v143, v143
	v_cvt_f32_i32_e32 v144, v144
	v_cvt_f32_i32_e32 v145, v145
	v_cvt_f32_i32_e32 v138, v138
	v_cvt_f32_i32_e32 v139, v139
	v_cvt_f32_i32_e32 v140, v140
	v_cvt_f32_i32_e32 v141, v141
	v_cvt_f32_i32_e32 v126, v126
	v_cvt_f32_i32_e32 v127, v127
	v_cvt_f32_i32_e32 v128, v128
	v_cvt_f32_i32_e32 v129, v129
	v_cvt_f32_i32_e32 v122, v122
	v_cvt_f32_i32_e32 v123, v123
	v_cvt_f32_i32_e32 v124, v124
	v_cvt_f32_i32_e32 v125, v125
	v_cvt_f32_i32_e32 v110, v110
	v_cvt_f32_i32_e32 v111, v111
	v_cvt_f32_i32_e32 v112, v112
	v_cvt_f32_i32_e32 v113, v113
	v_cvt_f32_i32_e32 v106, v106
	v_cvt_f32_i32_e32 v107, v107
	v_cvt_f32_i32_e32 v108, v108
	v_cvt_f32_i32_e32 v109, v109
	v_cvt_f32_i32_e32 v94, v94
	v_cvt_f32_i32_e32 v95, v95
	v_cvt_f32_i32_e32 v96, v96
	v_cvt_f32_i32_e32 v97, v97
	v_cvt_f32_i32_e32 v90, v90
	v_cvt_f32_i32_e32 v91, v91
	v_cvt_f32_i32_e32 v92, v92
	v_cvt_f32_i32_e32 v93, v93
	v_cvt_f32_i32_e32 v134, v134
	v_cvt_f32_i32_e32 v135, v135
	v_cvt_f32_i32_e32 v136, v136
	v_cvt_f32_i32_e32 v137, v137
	v_cvt_f32_i32_e32 v130, v130
	v_cvt_f32_i32_e32 v131, v131
	v_cvt_f32_i32_e32 v132, v132
	v_cvt_f32_i32_e32 v133, v133
	v_cvt_f32_i32_e32 v118, v118
	v_cvt_f32_i32_e32 v119, v119
	v_cvt_f32_i32_e32 v120, v120
	v_cvt_f32_i32_e32 v121, v121
	v_cvt_f32_i32_e32 v114, v114
	v_cvt_f32_i32_e32 v115, v115
	v_cvt_f32_i32_e32 v116, v116
	v_cvt_f32_i32_e32 v117, v117
	v_cvt_f32_i32_e32 v102, v102
	v_cvt_f32_i32_e32 v103, v103
	v_cvt_f32_i32_e32 v104, v104
	v_cvt_f32_i32_e32 v105, v105
	v_cvt_f32_i32_e32 v98, v98
	v_cvt_f32_i32_e32 v99, v99
	v_cvt_f32_i32_e32 v100, v100
	v_cvt_f32_i32_e32 v101, v101
	v_cvt_f32_i32_e32 v86, v86
	v_cvt_f32_i32_e32 v87, v87
	v_cvt_f32_i32_e32 v88, v88
	v_cvt_f32_i32_e32 v89, v89
	v_cvt_f32_i32_e32 v82, v82
	v_cvt_f32_i32_e32 v83, v83
	v_cvt_f32_i32_e32 v84, v84
	v_cvt_f32_i32_e32 v85, v85
	v_cvt_f32_i32_e32 v78, v78
	v_cvt_f32_i32_e32 v79, v79
	v_cvt_f32_i32_e32 v80, v80
	v_cvt_f32_i32_e32 v81, v81
	v_cvt_f32_i32_e32 v74, v74
	v_cvt_f32_i32_e32 v75, v75
	v_cvt_f32_i32_e32 v76, v76
	v_cvt_f32_i32_e32 v77, v77
	v_cvt_f32_i32_e32 v62, v62
	v_cvt_f32_i32_e32 v63, v63
	v_cvt_f32_i32_e32 v64, v64
	v_cvt_f32_i32_e32 v65, v65
	v_cvt_f32_i32_e32 v58, v58
	v_cvt_f32_i32_e32 v59, v59
	v_cvt_f32_i32_e32 v60, v60
	v_cvt_f32_i32_e32 v61, v61
	v_cvt_f32_i32_e32 v46, v46
	v_cvt_f32_i32_e32 v47, v47
	v_cvt_f32_i32_e32 v48, v48
	v_cvt_f32_i32_e32 v49, v49
	v_cvt_f32_i32_e32 v42, v42
	v_cvt_f32_i32_e32 v43, v43
	v_cvt_f32_i32_e32 v44, v44
	v_cvt_f32_i32_e32 v45, v45
	v_cvt_f32_i32_e32 v30, v30
	v_cvt_f32_i32_e32 v31, v31
	v_cvt_f32_i32_e32 v32, v32
	v_cvt_f32_i32_e32 v33, v33
	v_cvt_f32_i32_e32 v26, v26
	v_cvt_f32_i32_e32 v27, v27
	v_cvt_f32_i32_e32 v28, v28
	v_cvt_f32_i32_e32 v29, v29
	v_cvt_f32_i32_e32 v70, v70
	v_cvt_f32_i32_e32 v71, v71
	v_cvt_f32_i32_e32 v72, v72
	v_cvt_f32_i32_e32 v73, v73
	v_cvt_f32_i32_e32 v66, v66
	v_cvt_f32_i32_e32 v67, v67
	v_cvt_f32_i32_e32 v68, v68
	v_cvt_f32_i32_e32 v69, v69
	v_cvt_f32_i32_e32 v54, v54
	v_cvt_f32_i32_e32 v55, v55
	v_cvt_f32_i32_e32 v56, v56
	v_cvt_f32_i32_e32 v57, v57
	v_cvt_f32_i32_e32 v50, v50
	v_cvt_f32_i32_e32 v51, v51
	v_cvt_f32_i32_e32 v52, v52
	v_cvt_f32_i32_e32 v53, v53
	v_cvt_f32_i32_e32 v38, v38
	v_cvt_f32_i32_e32 v39, v39
	v_cvt_f32_i32_e32 v40, v40
	v_cvt_f32_i32_e32 v41, v41
	v_cvt_f32_i32_e32 v34, v34
	v_cvt_f32_i32_e32 v35, v35
	v_cvt_f32_i32_e32 v36, v36
	v_cvt_f32_i32_e32 v37, v37
	v_cvt_f32_i32_e32 v22, v22
	v_cvt_f32_i32_e32 v23, v23
	v_cvt_f32_i32_e32 v24, v24
	v_cvt_f32_i32_e32 v25, v25
	v_cvt_f32_i32_e32 v18, v18
	v_cvt_f32_i32_e32 v19, v19
	v_cvt_f32_i32_e32 v20, v20
	v_cvt_f32_i32_e32 v21, v21
	s_andn2_b64 vcc, exec, s[4:5]
	s_cbranch_vccnz .LBB0_936

.LBB0_1072:
	ds_read_b128 v[136:139], v152
	ds_read_b128 v[140:143], v152 offset:1024
	ds_read_b128 v[158:161], v152 offset:2048
	ds_read_b128 v[162:165], v152 offset:3072
	ds_read_b128 v[166:169], v153
	ds_read_b128 v[170:173], v153 offset:1024
	ds_read_b128 v[174:177], v153 offset:2048
	ds_read_b128 v[178:181], v153 offset:3072
	s_add_i32 s60, s55, 0xfffe0080
	s_cmp_eq_u32 s59, 4
	s_cselect_b32 s62, s1, s60
	s_cselect_b32 s61, s54, s58
	s_or_b32 s60, s62, 0x80
	s_mov_b32 m0, s42
	s_nop 0
	buffer_load_dwordx4 v146, s[12:15], s55 offen lds
	s_nop 0
	s_mov_b32 m0, s43
	s_nop 0
	buffer_load_dwordx4 v147, s[12:15], s55 offen lds
	ds_read_b128 v[182:185], v154
	ds_read_b128 v[186:189], v154 offset:1024
	ds_read_b128 v[190:193], v154 offset:2048
	ds_read_b128 v[194:197], v154 offset:3072
	ds_read_b128 v[198:201], v154 offset:4096
	ds_read_b128 v[202:205], v154 offset:5120
	ds_read_b128 v[206:209], v154 offset:6144
	ds_read_b128 v[210:213], v154 offset:7168
	s_waitcnt vmcnt(8)
	s_waitcnt lgkmcnt(0)
	s_barrier
	s_setprio 1
	v_mfma_i32_16x16x64_i8 v[126:129], v[136:139], v[182:185], v[126:129]
	v_mfma_i32_16x16x64_i8 v[122:125], v[158:161], v[182:185], v[122:125]
	v_mfma_i32_16x16x64_i8 v[118:121], v[136:139], v[190:193], v[118:121]
	v_mfma_i32_16x16x64_i8 v[114:117], v[158:161], v[190:193], v[114:117]
	v_mfma_i32_16x16x64_i8 v[110:113], v[136:139], v[198:201], v[110:113]
	v_mfma_i32_16x16x64_i8 v[106:109], v[158:161], v[198:201], v[106:109]
	v_mfma_i32_16x16x64_i8 v[102:105], v[136:139], v[206:209], v[102:105]
	v_mfma_i32_16x16x64_i8 v[98:101], v[158:161], v[206:209], v[98:101]
	v_mfma_i32_16x16x64_i8 v[126:129], v[140:143], v[186:189], v[126:129]
	v_mfma_i32_16x16x64_i8 v[122:125], v[162:165], v[186:189], v[122:125]
	v_mfma_i32_16x16x64_i8 v[118:121], v[140:143], v[194:197], v[118:121]
	v_mfma_i32_16x16x64_i8 v[114:117], v[162:165], v[194:197], v[114:117]
	v_mfma_i32_16x16x64_i8 v[110:113], v[140:143], v[202:205], v[110:113]
	v_mfma_i32_16x16x64_i8 v[106:109], v[162:165], v[202:205], v[106:109]
	v_mfma_i32_16x16x64_i8 v[102:105], v[140:143], v[210:213], v[102:105]
	v_mfma_i32_16x16x64_i8 v[98:101], v[162:165], v[210:213], v[98:101]
	s_setprio 0
	s_setprio 1
	v_mfma_i32_16x16x64_i8 v[94:97], v[166:169], v[182:185], v[94:97]
	v_mfma_i32_16x16x64_i8 v[90:93], v[174:177], v[182:185], v[90:93]
	v_mfma_i32_16x16x64_i8 v[86:89], v[166:169], v[190:193], v[86:89]
	v_mfma_i32_16x16x64_i8 v[82:85], v[174:177], v[190:193], v[82:85]
	v_mfma_i32_16x16x64_i8 v[78:81], v[166:169], v[198:201], v[78:81]
	v_mfma_i32_16x16x64_i8 v[74:77], v[174:177], v[198:201], v[74:77]
	v_mfma_i32_16x16x64_i8 v[70:73], v[166:169], v[206:209], v[70:73]
	v_mfma_i32_16x16x64_i8 v[66:69], v[174:177], v[206:209], v[66:69]
	v_mfma_i32_16x16x64_i8 v[94:97], v[170:173], v[186:189], v[94:97]
	v_mfma_i32_16x16x64_i8 v[90:93], v[178:181], v[186:189], v[90:93]
	v_mfma_i32_16x16x64_i8 v[86:89], v[170:173], v[194:197], v[86:89]
	v_mfma_i32_16x16x64_i8 v[82:85], v[178:181], v[194:197], v[82:85]
	v_mfma_i32_16x16x64_i8 v[78:81], v[170:173], v[202:205], v[78:81]
	v_mfma_i32_16x16x64_i8 v[74:77], v[178:181], v[202:205], v[74:77]
	v_mfma_i32_16x16x64_i8 v[70:73], v[170:173], v[210:213], v[70:73]
	v_mfma_i32_16x16x64_i8 v[66:69], v[178:181], v[210:213], v[66:69]
	s_barrier
	s_setprio 0
	ds_read_b128 v[182:185], v154 offset:16384
	ds_read_b128 v[186:189], v154 offset:17408
	s_mov_b32 m0, s27
	s_nop 0
	buffer_load_dwordx4 v144, s[8:11], s61 offen lds
	ds_read_b128 v[190:193], v154 offset:18432
	ds_read_b128 v[194:197], v154 offset:19456
	s_add_i32 s63, s61, 0x20000
	s_mov_b32 m0, s28
	s_nop 0
	buffer_load_dwordx4 v145, s[8:11], s61 offen lds
	ds_read_b128 v[198:201], v154 offset:20480
	ds_read_b128 v[202:205], v154 offset:21504
	s_nop 0
	s_mov_b32 m0, s29
	s_nop 0
	buffer_load_dwordx4 v144, s[8:11], s63 offen lds
	ds_read_b128 v[206:209], v154 offset:22528
	ds_read_b128 v[210:213], v154 offset:23552
	s_nop 0
	s_mov_b32 m0, s30
	s_nop 0
	buffer_load_dwordx4 v145, s[8:11], s63 offen lds
	s_nop 0
	s_mov_b32 m0, s26
	s_nop 0
	buffer_load_dwordx4 v146, s[12:15], s62 offen lds
	s_nop 0
	s_mov_b32 m0, s2
	s_nop 0
	buffer_load_dwordx4 v147, s[12:15], s62 offen lds
	s_waitcnt vmcnt(8)
	s_waitcnt lgkmcnt(0)
	s_barrier
	s_setprio 1
	v_mfma_i32_16x16x64_i8 v[62:65], v[136:139], v[182:185], v[62:65]
	v_mfma_i32_16x16x64_i8 v[58:61], v[158:161], v[182:185], v[58:61]
	v_mfma_i32_16x16x64_i8 v[54:57], v[136:139], v[190:193], v[54:57]
	v_mfma_i32_16x16x64_i8 v[50:53], v[158:161], v[190:193], v[50:53]
	v_mfma_i32_16x16x64_i8 v[46:49], v[136:139], v[198:201], v[46:49]
	v_mfma_i32_16x16x64_i8 v[42:45], v[158:161], v[198:201], v[42:45]
	v_mfma_i32_16x16x64_i8 v[38:41], v[136:139], v[206:209], v[38:41]
	v_mfma_i32_16x16x64_i8 v[34:37], v[158:161], v[206:209], v[34:37]
	v_mfma_i32_16x16x64_i8 v[62:65], v[140:143], v[186:189], v[62:65]
	v_mfma_i32_16x16x64_i8 v[58:61], v[162:165], v[186:189], v[58:61]
	v_mfma_i32_16x16x64_i8 v[54:57], v[140:143], v[194:197], v[54:57]
	v_mfma_i32_16x16x64_i8 v[50:53], v[162:165], v[194:197], v[50:53]
	v_mfma_i32_16x16x64_i8 v[46:49], v[140:143], v[202:205], v[46:49]
	v_mfma_i32_16x16x64_i8 v[42:45], v[162:165], v[202:205], v[42:45]
	v_mfma_i32_16x16x64_i8 v[38:41], v[140:143], v[210:213], v[38:41]
	v_mfma_i32_16x16x64_i8 v[34:37], v[162:165], v[210:213], v[34:37]
	s_setprio 0
	s_setprio 1
	v_mfma_i32_16x16x64_i8 v[30:33], v[166:169], v[182:185], v[30:33]
	v_mfma_i32_16x16x64_i8 v[26:29], v[174:177], v[182:185], v[26:29]
	v_mfma_i32_16x16x64_i8 v[22:25], v[166:169], v[190:193], v[22:25]
	v_mfma_i32_16x16x64_i8 v[18:21], v[174:177], v[190:193], v[18:21]
	v_mfma_i32_16x16x64_i8 v[14:17], v[166:169], v[198:201], v[14:17]
	v_mfma_i32_16x16x64_i8 v[10:13], v[174:177], v[198:201], v[10:13]
	v_mfma_i32_16x16x64_i8 v[6:9], v[166:169], v[206:209], v[6:9]
	v_mfma_i32_16x16x64_i8 v[2:5], v[174:177], v[206:209], v[2:5]
	v_mfma_i32_16x16x64_i8 v[30:33], v[170:173], v[186:189], v[30:33]
	v_mfma_i32_16x16x64_i8 v[26:29], v[178:181], v[186:189], v[26:29]
	v_mfma_i32_16x16x64_i8 v[22:25], v[170:173], v[194:197], v[22:25]
	v_mfma_i32_16x16x64_i8 v[18:21], v[178:181], v[194:197], v[18:21]
	v_mfma_i32_16x16x64_i8 v[14:17], v[170:173], v[202:205], v[14:17]
	v_mfma_i32_16x16x64_i8 v[10:13], v[178:181], v[202:205], v[10:13]
	v_mfma_i32_16x16x64_i8 v[6:9], v[170:173], v[210:213], v[6:9]
	v_mfma_i32_16x16x64_i8 v[2:5], v[178:181], v[210:213], v[2:5]
	s_barrier
	s_setprio 0
	ds_read_b128 v[136:139], v155
	ds_read_b128 v[140:143], v155 offset:1024
	ds_read_b128 v[158:161], v155 offset:2048
	ds_read_b128 v[162:165], v155 offset:3072
	ds_read_b128 v[166:169], v156
	ds_read_b128 v[170:173], v156 offset:1024
	ds_read_b128 v[174:177], v156 offset:2048
	ds_read_b128 v[178:181], v156 offset:3072
	s_add_i32 s62, s62, 0x20000
	s_mov_b32 m0, s3
	s_nop 0
	buffer_load_dwordx4 v146, s[12:15], s62 offen lds
	s_nop 0
	s_mov_b32 m0, s31
	s_nop 0
	buffer_load_dwordx4 v147, s[12:15], s62 offen lds
	ds_read_b128 v[182:185], v154 offset:32768
	ds_read_b128 v[186:189], v154 offset:33792
	ds_read_b128 v[190:193], v154 offset:34816
	ds_read_b128 v[194:197], v154 offset:35840
	ds_read_b128 v[198:201], v154 offset:36864
	ds_read_b128 v[202:205], v154 offset:37888
	ds_read_b128 v[206:209], v154 offset:38912
	ds_read_b128 v[210:213], v154 offset:39936
	s_waitcnt vmcnt(8)
	s_waitcnt lgkmcnt(0)
	s_barrier
	s_setprio 1
	v_mfma_i32_16x16x64_i8 v[126:129], v[136:139], v[182:185], v[126:129]
	v_mfma_i32_16x16x64_i8 v[122:125], v[158:161], v[182:185], v[122:125]
	v_mfma_i32_16x16x64_i8 v[118:121], v[136:139], v[190:193], v[118:121]
	v_mfma_i32_16x16x64_i8 v[114:117], v[158:161], v[190:193], v[114:117]
	v_mfma_i32_16x16x64_i8 v[110:113], v[136:139], v[198:201], v[110:113]
	v_mfma_i32_16x16x64_i8 v[106:109], v[158:161], v[198:201], v[106:109]
	v_mfma_i32_16x16x64_i8 v[102:105], v[136:139], v[206:209], v[102:105]
	v_mfma_i32_16x16x64_i8 v[98:101], v[158:161], v[206:209], v[98:101]
	v_mfma_i32_16x16x64_i8 v[126:129], v[140:143], v[186:189], v[126:129]
	v_mfma_i32_16x16x64_i8 v[122:125], v[162:165], v[186:189], v[122:125]
	v_mfma_i32_16x16x64_i8 v[118:121], v[140:143], v[194:197], v[118:121]
	v_mfma_i32_16x16x64_i8 v[114:117], v[162:165], v[194:197], v[114:117]
	v_mfma_i32_16x16x64_i8 v[110:113], v[140:143], v[202:205], v[110:113]
	v_mfma_i32_16x16x64_i8 v[106:109], v[162:165], v[202:205], v[106:109]
	v_mfma_i32_16x16x64_i8 v[102:105], v[140:143], v[210:213], v[102:105]
	v_mfma_i32_16x16x64_i8 v[98:101], v[162:165], v[210:213], v[98:101]
	s_setprio 0
	s_setprio 1
	v_mfma_i32_16x16x64_i8 v[94:97], v[166:169], v[182:185], v[94:97]
	v_mfma_i32_16x16x64_i8 v[90:93], v[174:177], v[182:185], v[90:93]
	v_mfma_i32_16x16x64_i8 v[86:89], v[166:169], v[190:193], v[86:89]
	v_mfma_i32_16x16x64_i8 v[82:85], v[174:177], v[190:193], v[82:85]
	v_mfma_i32_16x16x64_i8 v[78:81], v[166:169], v[198:201], v[78:81]
	v_mfma_i32_16x16x64_i8 v[74:77], v[174:177], v[198:201], v[74:77]
	v_mfma_i32_16x16x64_i8 v[70:73], v[166:169], v[206:209], v[70:73]
	v_mfma_i32_16x16x64_i8 v[66:69], v[174:177], v[206:209], v[66:69]
	v_mfma_i32_16x16x64_i8 v[94:97], v[170:173], v[186:189], v[94:97]
	v_mfma_i32_16x16x64_i8 v[90:93], v[178:181], v[186:189], v[90:93]
	v_mfma_i32_16x16x64_i8 v[86:89], v[170:173], v[194:197], v[86:89]
	v_mfma_i32_16x16x64_i8 v[82:85], v[178:181], v[194:197], v[82:85]
	v_mfma_i32_16x16x64_i8 v[78:81], v[170:173], v[202:205], v[78:81]
	v_mfma_i32_16x16x64_i8 v[74:77], v[178:181], v[202:205], v[74:77]
	v_mfma_i32_16x16x64_i8 v[70:73], v[170:173], v[210:213], v[70:73]
	v_mfma_i32_16x16x64_i8 v[66:69], v[178:181], v[210:213], v[66:69]
	s_barrier
	s_setprio 0
	ds_read_b128 v[182:185], v154 offset:49152
	ds_read_b128 v[186:189], v154 offset:50176
	s_or_b32 s62, s61, 0x80
	s_mov_b32 m0, s35
	s_nop 0
	buffer_load_dwordx4 v144, s[8:11], s62 offen lds
	ds_read_b128 v[190:193], v154 offset:51200
	ds_read_b128 v[194:197], v154 offset:52224
	s_add_i32 s61, s61, 0x20080
	s_mov_b32 m0, s36
	s_nop 0
	buffer_load_dwordx4 v145, s[8:11], s62 offen lds
	ds_read_b128 v[198:201], v154 offset:53248
	ds_read_b128 v[202:205], v154 offset:54272
	s_nop 0
	s_mov_b32 m0, s39
	s_nop 0
	buffer_load_dwordx4 v144, s[8:11], s61 offen lds
	ds_read_b128 v[206:209], v154 offset:55296
	ds_read_b128 v[210:213], v154 offset:56320
	s_nop 0
	s_mov_b32 m0, s40
	s_nop 0
	buffer_load_dwordx4 v145, s[8:11], s61 offen lds
	s_nop 0
	s_mov_b32 m0, s37
	s_nop 0
	buffer_load_dwordx4 v146, s[12:15], s60 offen lds
	s_nop 0
	s_mov_b32 m0, s38
	s_nop 0
	buffer_load_dwordx4 v147, s[12:15], s60 offen lds
	s_waitcnt vmcnt(8)
	s_waitcnt lgkmcnt(0)
	s_barrier
	s_setprio 1
	v_mfma_i32_16x16x64_i8 v[62:65], v[136:139], v[182:185], v[62:65]
	v_mfma_i32_16x16x64_i8 v[58:61], v[158:161], v[182:185], v[58:61]
	v_mfma_i32_16x16x64_i8 v[54:57], v[136:139], v[190:193], v[54:57]
	v_mfma_i32_16x16x64_i8 v[50:53], v[158:161], v[190:193], v[50:53]
	v_mfma_i32_16x16x64_i8 v[46:49], v[136:139], v[198:201], v[46:49]
	v_mfma_i32_16x16x64_i8 v[42:45], v[158:161], v[198:201], v[42:45]
	v_mfma_i32_16x16x64_i8 v[38:41], v[136:139], v[206:209], v[38:41]
	v_mfma_i32_16x16x64_i8 v[34:37], v[158:161], v[206:209], v[34:37]
	v_mfma_i32_16x16x64_i8 v[62:65], v[140:143], v[186:189], v[62:65]
	v_mfma_i32_16x16x64_i8 v[58:61], v[162:165], v[186:189], v[58:61]
	v_mfma_i32_16x16x64_i8 v[54:57], v[140:143], v[194:197], v[54:57]
	v_mfma_i32_16x16x64_i8 v[50:53], v[162:165], v[194:197], v[50:53]
	v_mfma_i32_16x16x64_i8 v[46:49], v[140:143], v[202:205], v[46:49]
	v_mfma_i32_16x16x64_i8 v[42:45], v[162:165], v[202:205], v[42:45]
	v_mfma_i32_16x16x64_i8 v[38:41], v[140:143], v[210:213], v[38:41]
	v_mfma_i32_16x16x64_i8 v[34:37], v[162:165], v[210:213], v[34:37]
	s_setprio 0
	s_setprio 1
	v_mfma_i32_16x16x64_i8 v[30:33], v[166:169], v[182:185], v[30:33]
	v_mfma_i32_16x16x64_i8 v[26:29], v[174:177], v[182:185], v[26:29]
	v_mfma_i32_16x16x64_i8 v[22:25], v[166:169], v[190:193], v[22:25]
	v_mfma_i32_16x16x64_i8 v[18:21], v[174:177], v[190:193], v[18:21]
	v_mfma_i32_16x16x64_i8 v[14:17], v[166:169], v[198:201], v[14:17]
	v_mfma_i32_16x16x64_i8 v[10:13], v[174:177], v[198:201], v[10:13]
	v_mfma_i32_16x16x64_i8 v[6:9], v[166:169], v[206:209], v[6:9]
	v_mfma_i32_16x16x64_i8 v[2:5], v[174:177], v[206:209], v[2:5]
	v_mfma_i32_16x16x64_i8 v[30:33], v[170:173], v[186:189], v[30:33]
	v_mfma_i32_16x16x64_i8 v[26:29], v[178:181], v[186:189], v[26:29]
	v_mfma_i32_16x16x64_i8 v[22:25], v[170:173], v[194:197], v[22:25]
	v_mfma_i32_16x16x64_i8 v[18:21], v[178:181], v[194:197], v[18:21]
	v_mfma_i32_16x16x64_i8 v[14:17], v[170:173], v[202:205], v[14:17]
	v_mfma_i32_16x16x64_i8 v[10:13], v[178:181], v[202:205], v[10:13]
	v_mfma_i32_16x16x64_i8 v[6:9], v[170:173], v[210:213], v[6:9]
	v_mfma_i32_16x16x64_i8 v[2:5], v[178:181], v[210:213], v[2:5]
	s_barrier
	s_setprio 0
	s_add_i32 s59, s59, 2
	s_addk_i32 s55, 0x100
	s_addk_i32 s58, 0x100
	s_cmp_gt_u32 s59, 5
	s_cbranch_scc0 .LBB0_1072
	s_and_b64 vcc, exec, s[20:21]
	s_cbranch_vccz .LBB0_1075
	s_barrier

.LBB0_1135:
	v_add_u32_e32 v150, 0x10000, v136
	v_add_u32_e32 v166, 0x14000, v136
	ds_read_b128 v[138:141], v150
	ds_read_b128 v[142:145], v150 offset:1024
	ds_read_b128 v[146:149], v150 offset:2048
	ds_read_b128 v[150:153], v150 offset:3072
	ds_read_b128 v[154:157], v166
	ds_read_b128 v[158:161], v166 offset:1024
	ds_read_b128 v[162:165], v166 offset:2048
	ds_read_b128 v[166:169], v166 offset:3072
	s_add_i32 s57, s36, s3
	s_add_i32 s56, s30, s3
	s_add_i32 s55, s57, 0x1600
	s_addk_i32 s56, 0x1600
	s_cmp_eq_u32 s3, 0
	s_cselect_b32 s58, s53, s55
	s_cselect_b32 s56, s54, s56
	s_add_i32 s55, s58, 0x80
	s_add_i32 s57, s57, 0xb1580
	s_mov_b32 m0, s46
	s_nop 0
	buffer_load_dwordx4 v134, s[16:19], s57 offen lds
	s_nop 0
	s_mov_b32 m0, s47
	s_nop 0
	buffer_load_dwordx4 v135, s[16:19], s57 offen lds
	ds_read_b128 v[170:173], v137
	ds_read_b128 v[174:177], v137 offset:1024
	ds_read_b128 v[178:181], v137 offset:2048
	ds_read_b128 v[182:185], v137 offset:3072
	ds_read_b128 v[186:189], v137 offset:4096
	ds_read_b128 v[190:193], v137 offset:5120
	ds_read_b128 v[194:197], v137 offset:6144
	ds_read_b128 v[198:201], v137 offset:7168
	s_waitcnt vmcnt(8)
	s_waitcnt lgkmcnt(0)
	s_barrier
	s_setprio 1
	v_mfma_f32_16x16x32_bf16 v[126:129], v[138:141], v[170:173], v[126:129]
	v_mfma_f32_16x16x32_bf16 v[122:125], v[146:149], v[170:173], v[122:125]
	v_mfma_f32_16x16x32_bf16 v[118:121], v[138:141], v[178:181], v[118:121]
	v_mfma_f32_16x16x32_bf16 v[106:109], v[146:149], v[178:181], v[106:109]
	v_mfma_f32_16x16x32_bf16 v[102:105], v[138:141], v[186:189], v[102:105]
	v_mfma_f32_16x16x32_bf16 v[90:93], v[146:149], v[186:189], v[90:93]
	v_mfma_f32_16x16x32_bf16 v[86:89], v[138:141], v[194:197], v[86:89]
	v_mfma_f32_16x16x32_bf16 v[74:77], v[146:149], v[194:197], v[74:77]
	v_mfma_f32_16x16x32_bf16 v[126:129], v[142:145], v[174:177], v[126:129]
	v_mfma_f32_16x16x32_bf16 v[122:125], v[150:153], v[174:177], v[122:125]
	v_mfma_f32_16x16x32_bf16 v[118:121], v[142:145], v[182:185], v[118:121]
	v_mfma_f32_16x16x32_bf16 v[106:109], v[150:153], v[182:185], v[106:109]
	v_mfma_f32_16x16x32_bf16 v[102:105], v[142:145], v[190:193], v[102:105]
	v_mfma_f32_16x16x32_bf16 v[90:93], v[150:153], v[190:193], v[90:93]
	v_mfma_f32_16x16x32_bf16 v[86:89], v[142:145], v[198:201], v[86:89]
	v_mfma_f32_16x16x32_bf16 v[74:77], v[150:153], v[198:201], v[74:77]
	s_setprio 0
	s_setprio 1
	v_mfma_f32_16x16x32_bf16 v[114:117], v[154:157], v[170:173], v[114:117]
	v_mfma_f32_16x16x32_bf16 v[110:113], v[162:165], v[170:173], v[110:113]
	v_mfma_f32_16x16x32_bf16 v[98:101], v[154:157], v[178:181], v[98:101]
	v_mfma_f32_16x16x32_bf16 v[94:97], v[162:165], v[178:181], v[94:97]
	v_mfma_f32_16x16x32_bf16 v[82:85], v[154:157], v[186:189], v[82:85]
	v_mfma_f32_16x16x32_bf16 v[78:81], v[162:165], v[186:189], v[78:81]
	v_mfma_f32_16x16x32_bf16 v[70:73], v[154:157], v[194:197], v[70:73]
	v_mfma_f32_16x16x32_bf16 v[66:69], v[162:165], v[194:197], v[66:69]
	v_mfma_f32_16x16x32_bf16 v[114:117], v[158:161], v[174:177], v[114:117]
	v_mfma_f32_16x16x32_bf16 v[110:113], v[166:169], v[174:177], v[110:113]
	v_mfma_f32_16x16x32_bf16 v[98:101], v[158:161], v[182:185], v[98:101]
	v_mfma_f32_16x16x32_bf16 v[94:97], v[166:169], v[182:185], v[94:97]
	v_mfma_f32_16x16x32_bf16 v[82:85], v[158:161], v[190:193], v[82:85]
	v_mfma_f32_16x16x32_bf16 v[78:81], v[166:169], v[190:193], v[78:81]
	v_mfma_f32_16x16x32_bf16 v[70:73], v[158:161], v[198:201], v[70:73]
	v_mfma_f32_16x16x32_bf16 v[66:69], v[166:169], v[198:201], v[66:69]
	s_barrier
	s_setprio 0
	ds_read_b128 v[170:173], v137 offset:16384
	ds_read_b128 v[174:177], v137 offset:17408
	s_mov_b32 m0, s29
	s_nop 0
	buffer_load_dwordx4 v134, s[12:15], s56 offen lds
	ds_read_b128 v[178:181], v137 offset:18432
	ds_read_b128 v[182:185], v137 offset:19456
	s_add_i32 s57, s56, 0xb0000
	s_mov_b32 m0, s33
	s_nop 0
	buffer_load_dwordx4 v135, s[12:15], s56 offen lds
	ds_read_b128 v[186:189], v137 offset:20480
	ds_read_b128 v[190:193], v137 offset:21504
	s_nop 0
	s_mov_b32 m0, s34
	s_nop 0
	buffer_load_dwordx4 v134, s[12:15], s57 offen lds
	ds_read_b128 v[194:197], v137 offset:22528
	ds_read_b128 v[198:201], v137 offset:23552
	s_nop 0
	s_mov_b32 m0, s35
	s_nop 0
	buffer_load_dwordx4 v135, s[12:15], s57 offen lds
	s_nop 0
	s_mov_b32 m0, s28
	s_nop 0
	buffer_load_dwordx4 v134, s[16:19], s58 offen lds
	s_nop 0
	s_mov_b32 m0, s37
	s_nop 0
	buffer_load_dwordx4 v135, s[16:19], s58 offen lds
	s_waitcnt vmcnt(8)
	s_waitcnt lgkmcnt(0)
	s_barrier
	s_setprio 1
	v_mfma_f32_16x16x32_bf16 v[62:65], v[138:141], v[170:173], v[62:65]
	v_mfma_f32_16x16x32_bf16 v[58:61], v[146:149], v[170:173], v[58:61]
	v_mfma_f32_16x16x32_bf16 v[54:57], v[138:141], v[178:181], v[54:57]
	v_mfma_f32_16x16x32_bf16 v[42:45], v[146:149], v[178:181], v[42:45]
	v_mfma_f32_16x16x32_bf16 v[38:41], v[138:141], v[186:189], v[38:41]
	v_mfma_f32_16x16x32_bf16 v[26:29], v[146:149], v[186:189], v[26:29]
	v_mfma_f32_16x16x32_bf16 v[18:21], v[138:141], v[194:197], v[18:21]
	v_mfma_f32_16x16x32_bf16 v[10:13], v[146:149], v[194:197], v[10:13]
	v_mfma_f32_16x16x32_bf16 v[62:65], v[142:145], v[174:177], v[62:65]
	v_mfma_f32_16x16x32_bf16 v[58:61], v[150:153], v[174:177], v[58:61]
	v_mfma_f32_16x16x32_bf16 v[54:57], v[142:145], v[182:185], v[54:57]
	v_mfma_f32_16x16x32_bf16 v[42:45], v[150:153], v[182:185], v[42:45]
	v_mfma_f32_16x16x32_bf16 v[38:41], v[142:145], v[190:193], v[38:41]
	v_mfma_f32_16x16x32_bf16 v[26:29], v[150:153], v[190:193], v[26:29]
	v_mfma_f32_16x16x32_bf16 v[18:21], v[142:145], v[198:201], v[18:21]
	v_mfma_f32_16x16x32_bf16 v[10:13], v[150:153], v[198:201], v[10:13]
	s_setprio 0
	s_setprio 1
	v_mfma_f32_16x16x32_bf16 v[50:53], v[154:157], v[170:173], v[50:53]
	v_mfma_f32_16x16x32_bf16 v[46:49], v[162:165], v[170:173], v[46:49]
	v_mfma_f32_16x16x32_bf16 v[34:37], v[154:157], v[178:181], v[34:37]
	v_mfma_f32_16x16x32_bf16 v[30:33], v[162:165], v[178:181], v[30:33]
	v_mfma_f32_16x16x32_bf16 v[22:25], v[154:157], v[186:189], v[22:25]
	v_mfma_f32_16x16x32_bf16 v[14:17], v[162:165], v[186:189], v[14:17]
	v_mfma_f32_16x16x32_bf16 v[6:9], v[154:157], v[194:197], v[6:9]
	v_mfma_f32_16x16x32_bf16 v[2:5], v[162:165], v[194:197], v[2:5]
	v_mfma_f32_16x16x32_bf16 v[50:53], v[158:161], v[174:177], v[50:53]
	v_mfma_f32_16x16x32_bf16 v[46:49], v[166:169], v[174:177], v[46:49]
	v_mfma_f32_16x16x32_bf16 v[34:37], v[158:161], v[182:185], v[34:37]
	v_mfma_f32_16x16x32_bf16 v[30:33], v[166:169], v[182:185], v[30:33]
	v_mfma_f32_16x16x32_bf16 v[22:25], v[158:161], v[190:193], v[22:25]
	v_mfma_f32_16x16x32_bf16 v[14:17], v[166:169], v[190:193], v[14:17]
	v_mfma_f32_16x16x32_bf16 v[6:9], v[158:161], v[198:201], v[6:9]
	v_mfma_f32_16x16x32_bf16 v[2:5], v[166:169], v[198:201], v[2:5]
	s_barrier
	s_setprio 0
	v_add_u32_e32 v150, 0x18000, v136
	v_add_u32_e32 v166, 0x1c000, v136
	ds_read_b128 v[138:141], v150
	ds_read_b128 v[142:145], v150 offset:1024
	ds_read_b128 v[146:149], v150 offset:2048
	ds_read_b128 v[150:153], v150 offset:3072
	ds_read_b128 v[154:157], v166
	ds_read_b128 v[158:161], v166 offset:1024
	ds_read_b128 v[162:165], v166 offset:2048
	ds_read_b128 v[166:169], v166 offset:3072
	s_add_i32 s57, s58, 0xb0000
	s_mov_b32 m0, s38
	s_nop 0
	buffer_load_dwordx4 v134, s[16:19], s57 offen lds
	s_nop 0
	s_mov_b32 m0, s39
	s_nop 0
	buffer_load_dwordx4 v135, s[16:19], s57 offen lds
	ds_read_b128 v[170:173], v137 offset:32768
	ds_read_b128 v[174:177], v137 offset:33792
	ds_read_b128 v[178:181], v137 offset:34816
	ds_read_b128 v[182:185], v137 offset:35840
	ds_read_b128 v[186:189], v137 offset:36864
	ds_read_b128 v[190:193], v137 offset:37888
	ds_read_b128 v[194:197], v137 offset:38912
	ds_read_b128 v[198:201], v137 offset:39936
	s_waitcnt vmcnt(8)
	s_waitcnt lgkmcnt(0)
	s_barrier
	s_setprio 1
	v_mfma_f32_16x16x32_bf16 v[126:129], v[138:141], v[170:173], v[126:129]
	v_mfma_f32_16x16x32_bf16 v[122:125], v[146:149], v[170:173], v[122:125]
	v_mfma_f32_16x16x32_bf16 v[118:121], v[138:141], v[178:181], v[118:121]
	v_mfma_f32_16x16x32_bf16 v[106:109], v[146:149], v[178:181], v[106:109]
	v_mfma_f32_16x16x32_bf16 v[102:105], v[138:141], v[186:189], v[102:105]
	v_mfma_f32_16x16x32_bf16 v[90:93], v[146:149], v[186:189], v[90:93]
	v_mfma_f32_16x16x32_bf16 v[86:89], v[138:141], v[194:197], v[86:89]
	v_mfma_f32_16x16x32_bf16 v[74:77], v[146:149], v[194:197], v[74:77]
	v_mfma_f32_16x16x32_bf16 v[126:129], v[142:145], v[174:177], v[126:129]
	v_mfma_f32_16x16x32_bf16 v[122:125], v[150:153], v[174:177], v[122:125]
	v_mfma_f32_16x16x32_bf16 v[118:121], v[142:145], v[182:185], v[118:121]
	v_mfma_f32_16x16x32_bf16 v[106:109], v[150:153], v[182:185], v[106:109]
	v_mfma_f32_16x16x32_bf16 v[102:105], v[142:145], v[190:193], v[102:105]
	v_mfma_f32_16x16x32_bf16 v[90:93], v[150:153], v[190:193], v[90:93]
	v_mfma_f32_16x16x32_bf16 v[86:89], v[142:145], v[198:201], v[86:89]
	v_mfma_f32_16x16x32_bf16 v[74:77], v[150:153], v[198:201], v[74:77]
	s_setprio 0
	s_setprio 1
	v_mfma_f32_16x16x32_bf16 v[114:117], v[154:157], v[170:173], v[114:117]
	v_mfma_f32_16x16x32_bf16 v[110:113], v[162:165], v[170:173], v[110:113]
	v_mfma_f32_16x16x32_bf16 v[98:101], v[154:157], v[178:181], v[98:101]
	v_mfma_f32_16x16x32_bf16 v[94:97], v[162:165], v[178:181], v[94:97]
	v_mfma_f32_16x16x32_bf16 v[82:85], v[154:157], v[186:189], v[82:85]
	v_mfma_f32_16x16x32_bf16 v[78:81], v[162:165], v[186:189], v[78:81]
	v_mfma_f32_16x16x32_bf16 v[70:73], v[154:157], v[194:197], v[70:73]
	v_mfma_f32_16x16x32_bf16 v[66:69], v[162:165], v[194:197], v[66:69]
	v_mfma_f32_16x16x32_bf16 v[114:117], v[158:161], v[174:177], v[114:117]
	v_mfma_f32_16x16x32_bf16 v[110:113], v[166:169], v[174:177], v[110:113]
	v_mfma_f32_16x16x32_bf16 v[98:101], v[158:161], v[182:185], v[98:101]
	v_mfma_f32_16x16x32_bf16 v[94:97], v[166:169], v[182:185], v[94:97]
	v_mfma_f32_16x16x32_bf16 v[82:85], v[158:161], v[190:193], v[82:85]
	v_mfma_f32_16x16x32_bf16 v[78:81], v[166:169], v[190:193], v[78:81]
	v_mfma_f32_16x16x32_bf16 v[70:73], v[158:161], v[198:201], v[70:73]
	v_mfma_f32_16x16x32_bf16 v[66:69], v[166:169], v[198:201], v[66:69]
	s_barrier
	s_setprio 0
	ds_read_b128 v[170:173], v137 offset:49152
	ds_read_b128 v[174:177], v137 offset:50176
	s_add_i32 s57, s56, 0x80
	s_mov_b32 m0, s40
	s_nop 0
	buffer_load_dwordx4 v134, s[12:15], s57 offen lds
	ds_read_b128 v[178:181], v137 offset:51200
	ds_read_b128 v[182:185], v137 offset:52224
	s_add_i32 s56, s56, 0xb0080
	s_mov_b32 m0, s41
	s_nop 0
	buffer_load_dwordx4 v135, s[12:15], s57 offen lds
	ds_read_b128 v[186:189], v137 offset:53248
	ds_read_b128 v[190:193], v137 offset:54272
	s_nop 0
	s_mov_b32 m0, s44
	s_nop 0
	buffer_load_dwordx4 v134, s[12:15], s56 offen lds
	ds_read_b128 v[194:197], v137 offset:55296
	ds_read_b128 v[198:201], v137 offset:56320
	s_nop 0
	s_mov_b32 m0, s45
	s_nop 0
	buffer_load_dwordx4 v135, s[12:15], s56 offen lds
	s_nop 0
	s_mov_b32 m0, s42
	s_nop 0
	buffer_load_dwordx4 v134, s[16:19], s55 offen lds
	s_nop 0
	s_mov_b32 m0, s43
	s_nop 0
	buffer_load_dwordx4 v135, s[16:19], s55 offen lds
	s_waitcnt vmcnt(8)
	s_waitcnt lgkmcnt(0)
	s_barrier
	s_setprio 1
	v_mfma_f32_16x16x32_bf16 v[62:65], v[138:141], v[170:173], v[62:65]
	v_mfma_f32_16x16x32_bf16 v[58:61], v[146:149], v[170:173], v[58:61]
	v_mfma_f32_16x16x32_bf16 v[54:57], v[138:141], v[178:181], v[54:57]
	v_mfma_f32_16x16x32_bf16 v[42:45], v[146:149], v[178:181], v[42:45]
	v_mfma_f32_16x16x32_bf16 v[38:41], v[138:141], v[186:189], v[38:41]
	v_mfma_f32_16x16x32_bf16 v[26:29], v[146:149], v[186:189], v[26:29]
	v_mfma_f32_16x16x32_bf16 v[18:21], v[138:141], v[194:197], v[18:21]
	v_mfma_f32_16x16x32_bf16 v[10:13], v[146:149], v[194:197], v[10:13]
	v_mfma_f32_16x16x32_bf16 v[62:65], v[142:145], v[174:177], v[62:65]
	v_mfma_f32_16x16x32_bf16 v[58:61], v[150:153], v[174:177], v[58:61]
	v_mfma_f32_16x16x32_bf16 v[54:57], v[142:145], v[182:185], v[54:57]
	v_mfma_f32_16x16x32_bf16 v[42:45], v[150:153], v[182:185], v[42:45]
	v_mfma_f32_16x16x32_bf16 v[38:41], v[142:145], v[190:193], v[38:41]
	v_mfma_f32_16x16x32_bf16 v[26:29], v[150:153], v[190:193], v[26:29]
	v_mfma_f32_16x16x32_bf16 v[18:21], v[142:145], v[198:201], v[18:21]
	v_mfma_f32_16x16x32_bf16 v[10:13], v[150:153], v[198:201], v[10:13]
	s_setprio 0
	s_setprio 1
	v_mfma_f32_16x16x32_bf16 v[50:53], v[154:157], v[170:173], v[50:53]
	v_mfma_f32_16x16x32_bf16 v[46:49], v[162:165], v[170:173], v[46:49]
	v_mfma_f32_16x16x32_bf16 v[34:37], v[154:157], v[178:181], v[34:37]
	v_mfma_f32_16x16x32_bf16 v[30:33], v[162:165], v[178:181], v[30:33]
	v_mfma_f32_16x16x32_bf16 v[22:25], v[154:157], v[186:189], v[22:25]
	v_mfma_f32_16x16x32_bf16 v[14:17], v[162:165], v[186:189], v[14:17]
	v_mfma_f32_16x16x32_bf16 v[6:9], v[154:157], v[194:197], v[6:9]
	v_mfma_f32_16x16x32_bf16 v[2:5], v[162:165], v[194:197], v[2:5]
	v_mfma_f32_16x16x32_bf16 v[50:53], v[158:161], v[174:177], v[50:53]
	v_mfma_f32_16x16x32_bf16 v[46:49], v[166:169], v[174:177], v[46:49]
	v_mfma_f32_16x16x32_bf16 v[34:37], v[158:161], v[182:185], v[34:37]
	v_mfma_f32_16x16x32_bf16 v[30:33], v[166:169], v[182:185], v[30:33]
	v_mfma_f32_16x16x32_bf16 v[22:25], v[158:161], v[190:193], v[22:25]
	v_mfma_f32_16x16x32_bf16 v[14:17], v[166:169], v[190:193], v[14:17]
	v_mfma_f32_16x16x32_bf16 v[6:9], v[158:161], v[198:201], v[6:9]
	v_mfma_f32_16x16x32_bf16 v[2:5], v[166:169], v[198:201], v[2:5]
	s_barrier
	s_setprio 0
	s_add_i32 s2, s2, 2
	s_addk_i32 s3, 0x100
	s_cmp_gt_u32 s2, 41
	s_cbranch_scc0 .LBB0_1135
	s_andn2_b64 vcc, exec, s[4:5]
	s_cbranch_vccnz .LBB0_1123
	v_mov_b32_e32 v2, 0
	s_mov_b32 s20, s50
	s_mov_b32 s25, s51
	s_mov_b32 s30, s54
	s_mov_b32 s36, s53
	s_mov_b32 s49, s52
	v_mov_b32_e32 v3, v2
	v_mov_b32_e32 v4, v2
	v_mov_b32_e32 v5, v2
	v_mov_b32_e32 v6, v2
	v_mov_b32_e32 v7, v2
	v_mov_b32_e32 v8, v2
	v_mov_b32_e32 v9, v2
	v_mov_b32_e32 v14, v2
	v_mov_b32_e32 v15, v2
	v_mov_b32_e32 v16, v2
	v_mov_b32_e32 v17, v2
	v_mov_b32_e32 v22, v2
	v_mov_b32_e32 v23, v2
	v_mov_b32_e32 v24, v2
	v_mov_b32_e32 v25, v2
	v_mov_b32_e32 v30, v2
	v_mov_b32_e32 v31, v2
	v_mov_b32_e32 v32, v2
	v_mov_b32_e32 v33, v2
	v_mov_b32_e32 v34, v2
	v_mov_b32_e32 v35, v2
	v_mov_b32_e32 v36, v2
	v_mov_b32_e32 v37, v2
	v_mov_b32_e32 v46, v2
	v_mov_b32_e32 v47, v2
	v_mov_b32_e32 v48, v2
	v_mov_b32_e32 v49, v2
	v_mov_b32_e32 v50, v2
	v_mov_b32_e32 v51, v2
	v_mov_b32_e32 v52, v2
	v_mov_b32_e32 v53, v2
	v_mov_b32_e32 v10, v2
	v_mov_b32_e32 v11, v2
	v_mov_b32_e32 v12, v2
	v_mov_b32_e32 v13, v2
	v_mov_b32_e32 v18, v2
	v_mov_b32_e32 v19, v2
	v_mov_b32_e32 v20, v2
	v_mov_b32_e32 v21, v2
	v_mov_b32_e32 v26, v2
	v_mov_b32_e32 v27, v2
	v_mov_b32_e32 v28, v2
	v_mov_b32_e32 v29, v2
	v_mov_b32_e32 v38, v2
	v_mov_b32_e32 v39, v2
	v_mov_b32_e32 v40, v2
	v_mov_b32_e32 v41, v2
	v_mov_b32_e32 v42, v2
	v_mov_b32_e32 v43, v2
	v_mov_b32_e32 v44, v2
	v_mov_b32_e32 v45, v2
	v_mov_b32_e32 v54, v2
	v_mov_b32_e32 v55, v2
	v_mov_b32_e32 v56, v2
	v_mov_b32_e32 v57, v2
	v_mov_b32_e32 v58, v2
	v_mov_b32_e32 v59, v2
	v_mov_b32_e32 v60, v2
	v_mov_b32_e32 v61, v2
	v_mov_b32_e32 v62, v2
	v_mov_b32_e32 v63, v2
	v_mov_b32_e32 v64, v2
	v_mov_b32_e32 v65, v2
	v_mov_b32_e32 v66, v2
	v_mov_b32_e32 v67, v2
	v_mov_b32_e32 v68, v2
	v_mov_b32_e32 v69, v2
	v_mov_b32_e32 v70, v2
	v_mov_b32_e32 v71, v2
	v_mov_b32_e32 v72, v2
	v_mov_b32_e32 v73, v2
	v_mov_b32_e32 v78, v2
	v_mov_b32_e32 v79, v2
	v_mov_b32_e32 v80, v2
	v_mov_b32_e32 v81, v2
	v_mov_b32_e32 v82, v2
	v_mov_b32_e32 v83, v2
	v_mov_b32_e32 v84, v2
	v_mov_b32_e32 v85, v2
	v_mov_b32_e32 v94, v2
	v_mov_b32_e32 v95, v2
	v_mov_b32_e32 v96, v2
	v_mov_b32_e32 v97, v2
	v_mov_b32_e32 v98, v2
	v_mov_b32_e32 v99, v2
	v_mov_b32_e32 v100, v2
	v_mov_b32_e32 v101, v2
	v_mov_b32_e32 v110, v2
	v_mov_b32_e32 v111, v2
	v_mov_b32_e32 v112, v2
	v_mov_b32_e32 v113, v2
	v_mov_b32_e32 v114, v2
	v_mov_b32_e32 v115, v2
	v_mov_b32_e32 v116, v2
	v_mov_b32_e32 v117, v2
	v_mov_b32_e32 v74, v2
	v_mov_b32_e32 v75, v2
	v_mov_b32_e32 v76, v2
	v_mov_b32_e32 v77, v2
	v_mov_b32_e32 v86, v2
	v_mov_b32_e32 v87, v2
	v_mov_b32_e32 v88, v2
	v_mov_b32_e32 v89, v2
	v_mov_b32_e32 v90, v2
	v_mov_b32_e32 v91, v2
	v_mov_b32_e32 v92, v2
	v_mov_b32_e32 v93, v2
	v_mov_b32_e32 v102, v2
	v_mov_b32_e32 v103, v2
	v_mov_b32_e32 v104, v2
	v_mov_b32_e32 v105, v2
	v_mov_b32_e32 v106, v2
	v_mov_b32_e32 v107, v2
	v_mov_b32_e32 v108, v2
	v_mov_b32_e32 v109, v2
	v_mov_b32_e32 v118, v2
	v_mov_b32_e32 v119, v2
	v_mov_b32_e32 v120, v2
	v_mov_b32_e32 v121, v2
	v_mov_b32_e32 v122, v2
	v_mov_b32_e32 v123, v2
	v_mov_b32_e32 v124, v2
	v_mov_b32_e32 v125, v2
	v_mov_b32_e32 v126, v2
	v_mov_b32_e32 v127, v2
	v_mov_b32_e32 v128, v2
	v_mov_b32_e32 v129, v2
	s_branch .LBB0_1123
